# v26 plus removal of the back-to-back s_setprio 0 / s_setprio 1 pairs that sat in the middle of each 32-MFMA block of the GEMM K loops
# speedup vs baseline: 1.0036x; 1.0036x over previous
.LBB0_307:
	s_add_u32 vcc_lo, s82, 0x80
	s_addc_u32 vcc_hi, s83, 0
	s_add_u32 s82, s42, 0x100
	s_addc_u32 s83, s43, 0
	s_mov_b32 s42, 0
	s_add_i32 s72, s42, 2
	s_add_u32 s73, vcc_lo, 0x80
	s_addc_u32 s43, vcc_hi, 0
	s_add_i32 s45, 0, 0x10000
	s_cmp_eq_u32 s63, s42
	s_cselect_b32 s43, s9, s43
	s_cselect_b32 s42, s8, s73
	v_add_u32_e32 v140, s45, v143
	s_cselect_b32 s75, s91, s83
	s_cselect_b32 s74, s90, s82
	s_add_i32 s73, 0, 0x14000
	ds_read_b128 v[146:149], v140
	ds_read_b128 v[150:153], v140 offset:1024
	ds_read_b128 v[154:157], v140 offset:2048
	ds_read_b128 v[158:161], v140 offset:3072
	v_add_u32_e32 v140, s73, v143
	ds_read_b128 v[162:165], v140
	ds_read_b128 v[166:169], v140 offset:1024
	ds_read_b128 v[170:173], v140 offset:2048
	ds_read_b128 v[174:177], v140 offset:3072
	v_lshl_add_u64 v[140:141], vcc, 0, v[136:137]
	s_add_i32 m0, s59, 0xc000
	ds_read_b128 v[178:181], v145
	ds_read_b128 v[182:185], v145 offset:1024
	ds_read_b128 v[186:189], v145 offset:2048
	ds_read_b128 v[190:193], v145 offset:3072
	ds_read_b128 v[202:205], v145 offset:4096
	ds_read_b128 v[206:209], v145 offset:5120
	ds_read_b128 v[220:223], v145 offset:6144
	ds_read_b128 v[224:227], v145 offset:7168
	global_load_lds_dwordx4 v[140:141], off
	v_lshl_add_u64 v[140:141], vcc, 0, v[138:139]
	s_add_i32 m0, s59, 0xe000
	s_nop 0
	global_load_lds_dwordx4 v[140:141], off
	s_waitcnt vmcnt(8)
	s_waitcnt lgkmcnt(0)
	s_barrier
	s_setprio 1
	s_waitcnt lgkmcnt(0)
	v_mfma_f32_16x16x32_bf16 v[126:129], v[146:149], v[178:181], 0
	v_mfma_f32_16x16x32_bf16 v[122:125], v[154:157], v[178:181], 0
	v_mfma_f32_16x16x32_bf16 v[118:121], v[146:149], v[186:189], 0
	v_mfma_f32_16x16x32_bf16 v[110:113], v[154:157], v[186:189], 0
	v_mfma_f32_16x16x32_bf16 v[102:105], v[146:149], v[202:205], 0
	v_mfma_f32_16x16x32_bf16 v[94:97], v[154:157], v[202:205], 0
	v_mfma_f32_16x16x32_bf16 v[86:89], v[146:149], v[220:223], 0
	v_mfma_f32_16x16x32_bf16 v[78:81], v[154:157], v[220:223], 0
	v_mfma_f32_16x16x32_bf16 v[126:129], v[150:153], v[182:185], v[126:129]
	v_mfma_f32_16x16x32_bf16 v[122:125], v[158:161], v[182:185], v[122:125]
	v_mfma_f32_16x16x32_bf16 v[118:121], v[150:153], v[190:193], v[118:121]
	v_mfma_f32_16x16x32_bf16 v[110:113], v[158:161], v[190:193], v[110:113]
	v_mfma_f32_16x16x32_bf16 v[102:105], v[150:153], v[206:209], v[102:105]
	v_mfma_f32_16x16x32_bf16 v[94:97], v[158:161], v[206:209], v[94:97]
	v_mfma_f32_16x16x32_bf16 v[86:89], v[150:153], v[224:227], v[86:89]
	v_mfma_f32_16x16x32_bf16 v[78:81], v[158:161], v[224:227], v[78:81]
	v_mfma_f32_16x16x32_bf16 v[114:117], v[162:165], v[178:181], 0
	v_mfma_f32_16x16x32_bf16 v[106:109], v[170:173], v[178:181], 0
	v_mfma_f32_16x16x32_bf16 v[98:101], v[162:165], v[186:189], 0
	v_mfma_f32_16x16x32_bf16 v[90:93], v[170:173], v[186:189], 0
	v_mfma_f32_16x16x32_bf16 v[82:85], v[162:165], v[202:205], 0
	v_mfma_f32_16x16x32_bf16 v[74:77], v[170:173], v[202:205], 0
	v_mfma_f32_16x16x32_bf16 v[70:73], v[162:165], v[220:223], 0
	v_mfma_f32_16x16x32_bf16 v[66:69], v[170:173], v[220:223], 0
	v_mfma_f32_16x16x32_bf16 v[114:117], v[166:169], v[182:185], v[114:117]
	v_mfma_f32_16x16x32_bf16 v[106:109], v[174:177], v[182:185], v[106:109]
	v_mfma_f32_16x16x32_bf16 v[98:101], v[166:169], v[190:193], v[98:101]
	v_mfma_f32_16x16x32_bf16 v[90:93], v[174:177], v[190:193], v[90:93]
	v_mfma_f32_16x16x32_bf16 v[82:85], v[166:169], v[206:209], v[82:85]
	v_mfma_f32_16x16x32_bf16 v[74:77], v[174:177], v[206:209], v[74:77]
	v_mfma_f32_16x16x32_bf16 v[70:73], v[166:169], v[224:227], v[70:73]
	v_mfma_f32_16x16x32_bf16 v[66:69], v[174:177], v[224:227], v[66:69]
	s_setprio 0
	s_barrier
	s_add_i32 s45, s45, s54
	v_lshl_add_u64 v[140:141], s[74:75], 0, v[0:1]
	s_mov_b32 m0, s45
	ds_read_b128 v[178:181], v145 offset:16384
	ds_read_b128 v[182:185], v145 offset:17408
	ds_read_b128 v[186:189], v145 offset:18432
	ds_read_b128 v[190:193], v145 offset:19456
	ds_read_b128 v[202:205], v145 offset:20480
	ds_read_b128 v[206:209], v145 offset:21504
	ds_read_b128 v[220:223], v145 offset:22528
	ds_read_b128 v[224:227], v145 offset:23552
	global_load_lds_dwordx4 v[140:141], off
	s_add_i32 m0, s45, 0x2000
	v_lshl_add_u64 v[194:195], s[74:75], 0, v[134:135]
	s_add_u32 s74, s74, s80
	s_addc_u32 s75, s75, 0
	s_add_i32 s45, s73, s54
	global_load_lds_dwordx4 v[194:195], off
	v_lshl_add_u64 v[198:199], s[74:75], 0, v[0:1]
	s_mov_b32 m0, s45
	v_lshl_add_u64 v[200:201], s[74:75], 0, v[134:135]
	global_load_lds_dwordx4 v[198:199], off
	s_add_i32 m0, s45, 0x2000
	v_lshl_add_u64 v[210:211], s[42:43], 0, v[130:131]
	global_load_lds_dwordx4 v[200:201], off
	s_mov_b32 m0, s59
	v_lshl_add_u64 v[212:213], s[42:43], 0, v[132:133]
	global_load_lds_dwordx4 v[210:211], off
	s_mov_b32 m0, s60
	s_nop 0
	global_load_lds_dwordx4 v[212:213], off
	s_waitcnt vmcnt(8)
	s_waitcnt lgkmcnt(0)
	s_barrier
	s_setprio 1
	s_waitcnt lgkmcnt(0)
	v_mfma_f32_16x16x32_bf16 v[62:65], v[146:149], v[178:181], 0
	v_mfma_f32_16x16x32_bf16 v[58:61], v[154:157], v[178:181], 0
	v_mfma_f32_16x16x32_bf16 v[54:57], v[146:149], v[186:189], 0
	v_mfma_f32_16x16x32_bf16 v[46:49], v[154:157], v[186:189], 0
	v_mfma_f32_16x16x32_bf16 v[38:41], v[146:149], v[202:205], 0
	v_mfma_f32_16x16x32_bf16 v[30:33], v[154:157], v[202:205], 0
	v_mfma_f32_16x16x32_bf16 v[22:25], v[146:149], v[220:223], 0
	v_mfma_f32_16x16x32_bf16 v[14:17], v[154:157], v[220:223], 0
	v_mfma_f32_16x16x32_bf16 v[62:65], v[150:153], v[182:185], v[62:65]
	v_mfma_f32_16x16x32_bf16 v[58:61], v[158:161], v[182:185], v[58:61]
	v_mfma_f32_16x16x32_bf16 v[54:57], v[150:153], v[190:193], v[54:57]
	v_mfma_f32_16x16x32_bf16 v[46:49], v[158:161], v[190:193], v[46:49]
	v_mfma_f32_16x16x32_bf16 v[38:41], v[150:153], v[206:209], v[38:41]
	v_mfma_f32_16x16x32_bf16 v[30:33], v[158:161], v[206:209], v[30:33]
	v_mfma_f32_16x16x32_bf16 v[22:25], v[150:153], v[224:227], v[22:25]
	v_mfma_f32_16x16x32_bf16 v[14:17], v[158:161], v[224:227], v[14:17]
	v_mfma_f32_16x16x32_bf16 v[50:53], v[162:165], v[178:181], 0
	v_mfma_f32_16x16x32_bf16 v[42:45], v[170:173], v[178:181], 0
	v_mfma_f32_16x16x32_bf16 v[34:37], v[162:165], v[186:189], 0
	v_mfma_f32_16x16x32_bf16 v[26:29], v[170:173], v[186:189], 0
	v_mfma_f32_16x16x32_bf16 v[18:21], v[162:165], v[202:205], 0
	v_mfma_f32_16x16x32_bf16 v[10:13], v[170:173], v[202:205], 0
	v_mfma_f32_16x16x32_bf16 v[6:9], v[162:165], v[220:223], 0
	v_mfma_f32_16x16x32_bf16 v[2:5], v[170:173], v[220:223], 0
	v_mfma_f32_16x16x32_bf16 v[50:53], v[166:169], v[182:185], v[50:53]
	v_mfma_f32_16x16x32_bf16 v[42:45], v[174:177], v[182:185], v[42:45]
	v_mfma_f32_16x16x32_bf16 v[34:37], v[166:169], v[190:193], v[34:37]
	v_mfma_f32_16x16x32_bf16 v[26:29], v[174:177], v[190:193], v[26:29]
	v_mfma_f32_16x16x32_bf16 v[18:21], v[166:169], v[206:209], v[18:21]
	v_mfma_f32_16x16x32_bf16 v[10:13], v[174:177], v[206:209], v[10:13]
	v_mfma_f32_16x16x32_bf16 v[6:9], v[166:169], v[224:227], v[6:9]
	v_mfma_f32_16x16x32_bf16 v[2:5], v[174:177], v[224:227], v[2:5]
	s_setprio 0
	s_barrier
	s_add_i32 s45, 0, 0x18000
	s_add_i32 s73, 0, 0x1c000
	v_add_u32_e32 v158, s45, v143
	v_add_u32_e32 v174, s73, v143
	ds_read_b128 v[146:149], v158
	ds_read_b128 v[150:153], v158 offset:1024
	ds_read_b128 v[154:157], v158 offset:2048
	ds_read_b128 v[158:161], v158 offset:3072
	ds_read_b128 v[162:165], v174
	ds_read_b128 v[166:169], v174 offset:1024
	ds_read_b128 v[170:173], v174 offset:2048
	ds_read_b128 v[174:177], v174 offset:3072
	s_add_u32 s42, s42, s80
	s_addc_u32 s43, s43, 0
	s_mov_b32 m0, s61
	v_lshl_add_u64 v[214:215], s[42:43], 0, v[130:131]
	ds_read_b128 v[178:181], v145 offset:32768
	ds_read_b128 v[182:185], v145 offset:33792
	ds_read_b128 v[186:189], v145 offset:34816
	ds_read_b128 v[190:193], v145 offset:35840
	ds_read_b128 v[202:205], v145 offset:36864
	ds_read_b128 v[206:209], v145 offset:37888
	ds_read_b128 v[220:223], v145 offset:38912
	ds_read_b128 v[224:227], v145 offset:39936
	global_load_lds_dwordx4 v[214:215], off
	v_lshl_add_u64 v[214:215], s[42:43], 0, v[132:133]
	s_mov_b32 m0, s62
	s_nop 0
	global_load_lds_dwordx4 v[214:215], off
	s_waitcnt vmcnt(8)
	s_waitcnt lgkmcnt(0)
	s_barrier
	s_setprio 1
	s_waitcnt lgkmcnt(0)
	v_mfma_f32_16x16x32_bf16 v[126:129], v[146:149], v[178:181], v[126:129]
	v_mfma_f32_16x16x32_bf16 v[122:125], v[154:157], v[178:181], v[122:125]
	v_mfma_f32_16x16x32_bf16 v[118:121], v[146:149], v[186:189], v[118:121]
	v_mfma_f32_16x16x32_bf16 v[110:113], v[154:157], v[186:189], v[110:113]
	v_mfma_f32_16x16x32_bf16 v[102:105], v[146:149], v[202:205], v[102:105]
	v_mfma_f32_16x16x32_bf16 v[94:97], v[154:157], v[202:205], v[94:97]
	v_mfma_f32_16x16x32_bf16 v[86:89], v[146:149], v[220:223], v[86:89]
	v_mfma_f32_16x16x32_bf16 v[78:81], v[154:157], v[220:223], v[78:81]
	v_mfma_f32_16x16x32_bf16 v[126:129], v[150:153], v[182:185], v[126:129]
	v_mfma_f32_16x16x32_bf16 v[122:125], v[158:161], v[182:185], v[122:125]
	v_mfma_f32_16x16x32_bf16 v[118:121], v[150:153], v[190:193], v[118:121]
	v_mfma_f32_16x16x32_bf16 v[110:113], v[158:161], v[190:193], v[110:113]
	v_mfma_f32_16x16x32_bf16 v[102:105], v[150:153], v[206:209], v[102:105]
	v_mfma_f32_16x16x32_bf16 v[94:97], v[158:161], v[206:209], v[94:97]
	v_mfma_f32_16x16x32_bf16 v[86:89], v[150:153], v[224:227], v[86:89]
	v_mfma_f32_16x16x32_bf16 v[78:81], v[158:161], v[224:227], v[78:81]
	v_mfma_f32_16x16x32_bf16 v[114:117], v[162:165], v[178:181], v[114:117]
	v_mfma_f32_16x16x32_bf16 v[106:109], v[170:173], v[178:181], v[106:109]
	v_mfma_f32_16x16x32_bf16 v[98:101], v[162:165], v[186:189], v[98:101]
	v_mfma_f32_16x16x32_bf16 v[90:93], v[170:173], v[186:189], v[90:93]
	v_mfma_f32_16x16x32_bf16 v[82:85], v[162:165], v[202:205], v[82:85]
	v_mfma_f32_16x16x32_bf16 v[74:77], v[170:173], v[202:205], v[74:77]
	v_mfma_f32_16x16x32_bf16 v[70:73], v[162:165], v[220:223], v[70:73]
	v_mfma_f32_16x16x32_bf16 v[66:69], v[170:173], v[220:223], v[66:69]
	v_mfma_f32_16x16x32_bf16 v[114:117], v[166:169], v[182:185], v[114:117]
	v_mfma_f32_16x16x32_bf16 v[106:109], v[174:177], v[182:185], v[106:109]
	v_mfma_f32_16x16x32_bf16 v[98:101], v[166:169], v[190:193], v[98:101]
	v_mfma_f32_16x16x32_bf16 v[90:93], v[174:177], v[190:193], v[90:93]
	v_mfma_f32_16x16x32_bf16 v[82:85], v[166:169], v[206:209], v[82:85]
	v_mfma_f32_16x16x32_bf16 v[74:77], v[174:177], v[206:209], v[74:77]
	v_mfma_f32_16x16x32_bf16 v[70:73], v[166:169], v[224:227], v[70:73]
	v_mfma_f32_16x16x32_bf16 v[66:69], v[174:177], v[224:227], v[66:69]
	s_setprio 0
	s_barrier
	s_add_i32 s42, s45, s54
	v_lshl_add_u64 v[140:141], v[140:141], 0, s[84:85]
	s_mov_b32 m0, s42
	ds_read_b128 v[178:181], v145 offset:49152
	ds_read_b128 v[182:185], v145 offset:50176
	ds_read_b128 v[186:189], v145 offset:51200
	ds_read_b128 v[190:193], v145 offset:52224
	ds_read_b128 v[202:205], v145 offset:53248
	ds_read_b128 v[206:209], v145 offset:54272
	ds_read_b128 v[220:223], v145 offset:55296
	ds_read_b128 v[224:227], v145 offset:56320
	global_load_lds_dwordx4 v[140:141], off
	v_lshl_add_u64 v[140:141], v[194:195], 0, s[84:85]
	s_add_i32 m0, s42, 0x2000
	s_add_i32 s42, s73, s54
	global_load_lds_dwordx4 v[140:141], off
	v_lshl_add_u64 v[140:141], v[198:199], 0, s[84:85]
	s_mov_b32 m0, s42
	s_nop 0
	global_load_lds_dwordx4 v[140:141], off
	v_lshl_add_u64 v[140:141], v[200:201], 0, s[84:85]
	s_add_i32 m0, s42, 0x2000
	s_nop 0
	global_load_lds_dwordx4 v[140:141], off
	v_lshl_add_u64 v[140:141], v[210:211], 0, s[84:85]
	s_mov_b32 m0, s64
	s_nop 0
	global_load_lds_dwordx4 v[140:141], off
	v_lshl_add_u64 v[140:141], v[212:213], 0, s[84:85]
	s_mov_b32 m0, s65
	s_nop 0
	global_load_lds_dwordx4 v[140:141], off
	s_waitcnt vmcnt(8)
	s_waitcnt lgkmcnt(0)
	s_barrier
	s_setprio 1
	s_waitcnt lgkmcnt(0)
	v_mfma_f32_16x16x32_bf16 v[62:65], v[146:149], v[178:181], v[62:65]
	v_mfma_f32_16x16x32_bf16 v[58:61], v[154:157], v[178:181], v[58:61]
	v_mfma_f32_16x16x32_bf16 v[54:57], v[146:149], v[186:189], v[54:57]
	v_mfma_f32_16x16x32_bf16 v[46:49], v[154:157], v[186:189], v[46:49]
	v_mfma_f32_16x16x32_bf16 v[38:41], v[146:149], v[202:205], v[38:41]
	v_mfma_f32_16x16x32_bf16 v[30:33], v[154:157], v[202:205], v[30:33]
	v_mfma_f32_16x16x32_bf16 v[22:25], v[146:149], v[220:223], v[22:25]
	v_mfma_f32_16x16x32_bf16 v[14:17], v[154:157], v[220:223], v[14:17]
	v_mfma_f32_16x16x32_bf16 v[62:65], v[150:153], v[182:185], v[62:65]
	v_mfma_f32_16x16x32_bf16 v[58:61], v[158:161], v[182:185], v[58:61]
	v_mfma_f32_16x16x32_bf16 v[54:57], v[150:153], v[190:193], v[54:57]
	v_mfma_f32_16x16x32_bf16 v[46:49], v[158:161], v[190:193], v[46:49]
	v_mfma_f32_16x16x32_bf16 v[38:41], v[150:153], v[206:209], v[38:41]
	v_mfma_f32_16x16x32_bf16 v[30:33], v[158:161], v[206:209], v[30:33]
	v_mfma_f32_16x16x32_bf16 v[22:25], v[150:153], v[224:227], v[22:25]
	v_mfma_f32_16x16x32_bf16 v[14:17], v[158:161], v[224:227], v[14:17]
	v_mfma_f32_16x16x32_bf16 v[50:53], v[162:165], v[178:181], v[50:53]
	v_mfma_f32_16x16x32_bf16 v[42:45], v[170:173], v[178:181], v[42:45]
	v_mfma_f32_16x16x32_bf16 v[34:37], v[162:165], v[186:189], v[34:37]
	v_mfma_f32_16x16x32_bf16 v[26:29], v[170:173], v[186:189], v[26:29]
	v_mfma_f32_16x16x32_bf16 v[18:21], v[162:165], v[202:205], v[18:21]
	v_mfma_f32_16x16x32_bf16 v[10:13], v[170:173], v[202:205], v[10:13]
	v_mfma_f32_16x16x32_bf16 v[6:9], v[162:165], v[220:223], v[6:9]
	v_mfma_f32_16x16x32_bf16 v[2:5], v[170:173], v[220:223], v[2:5]
	v_mfma_f32_16x16x32_bf16 v[50:53], v[166:169], v[182:185], v[50:53]
	v_mfma_f32_16x16x32_bf16 v[42:45], v[174:177], v[182:185], v[42:45]
	v_mfma_f32_16x16x32_bf16 v[34:37], v[166:169], v[190:193], v[34:37]
	v_mfma_f32_16x16x32_bf16 v[26:29], v[174:177], v[190:193], v[26:29]
	v_mfma_f32_16x16x32_bf16 v[18:21], v[166:169], v[206:209], v[18:21]
	v_mfma_f32_16x16x32_bf16 v[10:13], v[174:177], v[206:209], v[10:13]
	v_mfma_f32_16x16x32_bf16 v[6:9], v[166:169], v[224:227], v[6:9]
	v_mfma_f32_16x16x32_bf16 v[2:5], v[174:177], v[224:227], v[2:5]
	s_setprio 0
	s_barrier
	s_add_u32 vcc_lo, vcc_lo, 0x100
	s_addc_u32 vcc_hi, vcc_hi, 0
	s_add_u32 s82, s82, 0x100
	s_addc_u32 s83, s83, 0
	s_cmp_ge_u32 s72, s66
	s_mov_b32 s42, s72
	s_cbranch_scc1 .Lpeel_exit_bf
.LBB0_308:
	s_add_i32 s72, s42, 2
	s_add_u32 s73, vcc_lo, 0x80
	s_addc_u32 s43, vcc_hi, 0
	s_add_i32 s45, 0, 0x10000
	s_cmp_eq_u32 s63, s42
	s_cselect_b32 s43, s9, s43
	s_cselect_b32 s42, s8, s73
	v_add_u32_e32 v140, s45, v143
	s_cselect_b32 s75, s91, s83
	s_cselect_b32 s74, s90, s82
	s_add_i32 s73, 0, 0x14000
	ds_read_b128 v[146:149], v140
	ds_read_b128 v[150:153], v140 offset:1024
	ds_read_b128 v[154:157], v140 offset:2048
	ds_read_b128 v[158:161], v140 offset:3072
	v_add_u32_e32 v140, s73, v143
	ds_read_b128 v[162:165], v140
	ds_read_b128 v[166:169], v140 offset:1024
	ds_read_b128 v[170:173], v140 offset:2048
	ds_read_b128 v[174:177], v140 offset:3072
	v_lshl_add_u64 v[140:141], vcc, 0, v[136:137]
	s_add_i32 m0, s59, 0xc000
	ds_read_b128 v[178:181], v145
	ds_read_b128 v[182:185], v145 offset:1024
	ds_read_b128 v[186:189], v145 offset:2048
	ds_read_b128 v[190:193], v145 offset:3072
	ds_read_b128 v[202:205], v145 offset:4096
	ds_read_b128 v[206:209], v145 offset:5120
	ds_read_b128 v[220:223], v145 offset:6144
	ds_read_b128 v[224:227], v145 offset:7168
	global_load_lds_dwordx4 v[140:141], off
	v_lshl_add_u64 v[140:141], vcc, 0, v[138:139]
	s_add_i32 m0, s59, 0xe000
	s_nop 0
	global_load_lds_dwordx4 v[140:141], off
	s_waitcnt vmcnt(8)
	s_waitcnt lgkmcnt(0)
	s_barrier
	s_setprio 1
	s_waitcnt lgkmcnt(0)
	v_mfma_f32_16x16x32_bf16 v[126:129], v[146:149], v[178:181], v[126:129]
	v_mfma_f32_16x16x32_bf16 v[122:125], v[154:157], v[178:181], v[122:125]
	v_mfma_f32_16x16x32_bf16 v[118:121], v[146:149], v[186:189], v[118:121]
	v_mfma_f32_16x16x32_bf16 v[110:113], v[154:157], v[186:189], v[110:113]
	v_mfma_f32_16x16x32_bf16 v[102:105], v[146:149], v[202:205], v[102:105]
	v_mfma_f32_16x16x32_bf16 v[94:97], v[154:157], v[202:205], v[94:97]
	v_mfma_f32_16x16x32_bf16 v[86:89], v[146:149], v[220:223], v[86:89]
	v_mfma_f32_16x16x32_bf16 v[78:81], v[154:157], v[220:223], v[78:81]
	v_mfma_f32_16x16x32_bf16 v[126:129], v[150:153], v[182:185], v[126:129]
	v_mfma_f32_16x16x32_bf16 v[122:125], v[158:161], v[182:185], v[122:125]
	v_mfma_f32_16x16x32_bf16 v[118:121], v[150:153], v[190:193], v[118:121]
	v_mfma_f32_16x16x32_bf16 v[110:113], v[158:161], v[190:193], v[110:113]
	v_mfma_f32_16x16x32_bf16 v[102:105], v[150:153], v[206:209], v[102:105]
	v_mfma_f32_16x16x32_bf16 v[94:97], v[158:161], v[206:209], v[94:97]
	v_mfma_f32_16x16x32_bf16 v[86:89], v[150:153], v[224:227], v[86:89]
	v_mfma_f32_16x16x32_bf16 v[78:81], v[158:161], v[224:227], v[78:81]
	v_mfma_f32_16x16x32_bf16 v[114:117], v[162:165], v[178:181], v[114:117]
	v_mfma_f32_16x16x32_bf16 v[106:109], v[170:173], v[178:181], v[106:109]
	v_mfma_f32_16x16x32_bf16 v[98:101], v[162:165], v[186:189], v[98:101]
	v_mfma_f32_16x16x32_bf16 v[90:93], v[170:173], v[186:189], v[90:93]
	v_mfma_f32_16x16x32_bf16 v[82:85], v[162:165], v[202:205], v[82:85]
	v_mfma_f32_16x16x32_bf16 v[74:77], v[170:173], v[202:205], v[74:77]
	v_mfma_f32_16x16x32_bf16 v[70:73], v[162:165], v[220:223], v[70:73]
	v_mfma_f32_16x16x32_bf16 v[66:69], v[170:173], v[220:223], v[66:69]
	v_mfma_f32_16x16x32_bf16 v[114:117], v[166:169], v[182:185], v[114:117]
	v_mfma_f32_16x16x32_bf16 v[106:109], v[174:177], v[182:185], v[106:109]
	v_mfma_f32_16x16x32_bf16 v[98:101], v[166:169], v[190:193], v[98:101]
	v_mfma_f32_16x16x32_bf16 v[90:93], v[174:177], v[190:193], v[90:93]
	v_mfma_f32_16x16x32_bf16 v[82:85], v[166:169], v[206:209], v[82:85]
	v_mfma_f32_16x16x32_bf16 v[74:77], v[174:177], v[206:209], v[74:77]
	v_mfma_f32_16x16x32_bf16 v[70:73], v[166:169], v[224:227], v[70:73]
	v_mfma_f32_16x16x32_bf16 v[66:69], v[174:177], v[224:227], v[66:69]
	s_setprio 0
	s_barrier
	s_add_i32 s45, s45, s54
	v_lshl_add_u64 v[140:141], s[74:75], 0, v[0:1]
	s_mov_b32 m0, s45
	ds_read_b128 v[178:181], v145 offset:16384
	ds_read_b128 v[182:185], v145 offset:17408
	ds_read_b128 v[186:189], v145 offset:18432
	ds_read_b128 v[190:193], v145 offset:19456
	ds_read_b128 v[202:205], v145 offset:20480
	ds_read_b128 v[206:209], v145 offset:21504
	ds_read_b128 v[220:223], v145 offset:22528
	ds_read_b128 v[224:227], v145 offset:23552
	global_load_lds_dwordx4 v[140:141], off
	s_add_i32 m0, s45, 0x2000
	v_lshl_add_u64 v[194:195], s[74:75], 0, v[134:135]
	s_add_u32 s74, s74, s80
	s_addc_u32 s75, s75, 0
	s_add_i32 s45, s73, s54
	global_load_lds_dwordx4 v[194:195], off
	v_lshl_add_u64 v[198:199], s[74:75], 0, v[0:1]
	s_mov_b32 m0, s45
	v_lshl_add_u64 v[200:201], s[74:75], 0, v[134:135]
	global_load_lds_dwordx4 v[198:199], off
	s_add_i32 m0, s45, 0x2000
	v_lshl_add_u64 v[210:211], s[42:43], 0, v[130:131]
	global_load_lds_dwordx4 v[200:201], off
	s_mov_b32 m0, s59
	v_lshl_add_u64 v[212:213], s[42:43], 0, v[132:133]
	global_load_lds_dwordx4 v[210:211], off
	s_mov_b32 m0, s60
	s_nop 0
	global_load_lds_dwordx4 v[212:213], off
	s_waitcnt vmcnt(8)
	s_waitcnt lgkmcnt(0)
	s_barrier
	s_setprio 1
	s_waitcnt lgkmcnt(0)
	v_mfma_f32_16x16x32_bf16 v[62:65], v[146:149], v[178:181], v[62:65]
	v_mfma_f32_16x16x32_bf16 v[58:61], v[154:157], v[178:181], v[58:61]
	v_mfma_f32_16x16x32_bf16 v[54:57], v[146:149], v[186:189], v[54:57]
	v_mfma_f32_16x16x32_bf16 v[46:49], v[154:157], v[186:189], v[46:49]
	v_mfma_f32_16x16x32_bf16 v[38:41], v[146:149], v[202:205], v[38:41]
	v_mfma_f32_16x16x32_bf16 v[30:33], v[154:157], v[202:205], v[30:33]
	v_mfma_f32_16x16x32_bf16 v[22:25], v[146:149], v[220:223], v[22:25]
	v_mfma_f32_16x16x32_bf16 v[14:17], v[154:157], v[220:223], v[14:17]
	v_mfma_f32_16x16x32_bf16 v[62:65], v[150:153], v[182:185], v[62:65]
	v_mfma_f32_16x16x32_bf16 v[58:61], v[158:161], v[182:185], v[58:61]
	v_mfma_f32_16x16x32_bf16 v[54:57], v[150:153], v[190:193], v[54:57]
	v_mfma_f32_16x16x32_bf16 v[46:49], v[158:161], v[190:193], v[46:49]
	v_mfma_f32_16x16x32_bf16 v[38:41], v[150:153], v[206:209], v[38:41]
	v_mfma_f32_16x16x32_bf16 v[30:33], v[158:161], v[206:209], v[30:33]
	v_mfma_f32_16x16x32_bf16 v[22:25], v[150:153], v[224:227], v[22:25]
	v_mfma_f32_16x16x32_bf16 v[14:17], v[158:161], v[224:227], v[14:17]
	v_mfma_f32_16x16x32_bf16 v[50:53], v[162:165], v[178:181], v[50:53]
	v_mfma_f32_16x16x32_bf16 v[42:45], v[170:173], v[178:181], v[42:45]
	v_mfma_f32_16x16x32_bf16 v[34:37], v[162:165], v[186:189], v[34:37]
	v_mfma_f32_16x16x32_bf16 v[26:29], v[170:173], v[186:189], v[26:29]
	v_mfma_f32_16x16x32_bf16 v[18:21], v[162:165], v[202:205], v[18:21]
	v_mfma_f32_16x16x32_bf16 v[10:13], v[170:173], v[202:205], v[10:13]
	v_mfma_f32_16x16x32_bf16 v[6:9], v[162:165], v[220:223], v[6:9]
	v_mfma_f32_16x16x32_bf16 v[2:5], v[170:173], v[220:223], v[2:5]
	v_mfma_f32_16x16x32_bf16 v[50:53], v[166:169], v[182:185], v[50:53]
	v_mfma_f32_16x16x32_bf16 v[42:45], v[174:177], v[182:185], v[42:45]
	v_mfma_f32_16x16x32_bf16 v[34:37], v[166:169], v[190:193], v[34:37]
	v_mfma_f32_16x16x32_bf16 v[26:29], v[174:177], v[190:193], v[26:29]
	v_mfma_f32_16x16x32_bf16 v[18:21], v[166:169], v[206:209], v[18:21]
	v_mfma_f32_16x16x32_bf16 v[10:13], v[174:177], v[206:209], v[10:13]
	v_mfma_f32_16x16x32_bf16 v[6:9], v[166:169], v[224:227], v[6:9]
	v_mfma_f32_16x16x32_bf16 v[2:5], v[174:177], v[224:227], v[2:5]
	s_setprio 0
	s_barrier
	s_add_i32 s45, 0, 0x18000
	s_add_i32 s73, 0, 0x1c000
	v_add_u32_e32 v158, s45, v143
	v_add_u32_e32 v174, s73, v143
	ds_read_b128 v[146:149], v158
	ds_read_b128 v[150:153], v158 offset:1024
	ds_read_b128 v[154:157], v158 offset:2048
	ds_read_b128 v[158:161], v158 offset:3072
	ds_read_b128 v[162:165], v174
	ds_read_b128 v[166:169], v174 offset:1024
	ds_read_b128 v[170:173], v174 offset:2048
	ds_read_b128 v[174:177], v174 offset:3072
	s_add_u32 s42, s42, s80
	s_addc_u32 s43, s43, 0
	s_mov_b32 m0, s61
	v_lshl_add_u64 v[214:215], s[42:43], 0, v[130:131]
	ds_read_b128 v[178:181], v145 offset:32768
	ds_read_b128 v[182:185], v145 offset:33792
	ds_read_b128 v[186:189], v145 offset:34816
	ds_read_b128 v[190:193], v145 offset:35840
	ds_read_b128 v[202:205], v145 offset:36864
	ds_read_b128 v[206:209], v145 offset:37888
	ds_read_b128 v[220:223], v145 offset:38912
	ds_read_b128 v[224:227], v145 offset:39936
	global_load_lds_dwordx4 v[214:215], off
	v_lshl_add_u64 v[214:215], s[42:43], 0, v[132:133]
	s_mov_b32 m0, s62
	s_nop 0
	global_load_lds_dwordx4 v[214:215], off
	s_waitcnt vmcnt(8)
	s_waitcnt lgkmcnt(0)
	s_barrier
	s_setprio 1
	s_waitcnt lgkmcnt(0)
	v_mfma_f32_16x16x32_bf16 v[126:129], v[146:149], v[178:181], v[126:129]
	v_mfma_f32_16x16x32_bf16 v[122:125], v[154:157], v[178:181], v[122:125]
	v_mfma_f32_16x16x32_bf16 v[118:121], v[146:149], v[186:189], v[118:121]
	v_mfma_f32_16x16x32_bf16 v[110:113], v[154:157], v[186:189], v[110:113]
	v_mfma_f32_16x16x32_bf16 v[102:105], v[146:149], v[202:205], v[102:105]
	v_mfma_f32_16x16x32_bf16 v[94:97], v[154:157], v[202:205], v[94:97]
	v_mfma_f32_16x16x32_bf16 v[86:89], v[146:149], v[220:223], v[86:89]
	v_mfma_f32_16x16x32_bf16 v[78:81], v[154:157], v[220:223], v[78:81]
	v_mfma_f32_16x16x32_bf16 v[126:129], v[150:153], v[182:185], v[126:129]
	v_mfma_f32_16x16x32_bf16 v[122:125], v[158:161], v[182:185], v[122:125]
	v_mfma_f32_16x16x32_bf16 v[118:121], v[150:153], v[190:193], v[118:121]
	v_mfma_f32_16x16x32_bf16 v[110:113], v[158:161], v[190:193], v[110:113]
	v_mfma_f32_16x16x32_bf16 v[102:105], v[150:153], v[206:209], v[102:105]
	v_mfma_f32_16x16x32_bf16 v[94:97], v[158:161], v[206:209], v[94:97]
	v_mfma_f32_16x16x32_bf16 v[86:89], v[150:153], v[224:227], v[86:89]
	v_mfma_f32_16x16x32_bf16 v[78:81], v[158:161], v[224:227], v[78:81]
	v_mfma_f32_16x16x32_bf16 v[114:117], v[162:165], v[178:181], v[114:117]
	v_mfma_f32_16x16x32_bf16 v[106:109], v[170:173], v[178:181], v[106:109]
	v_mfma_f32_16x16x32_bf16 v[98:101], v[162:165], v[186:189], v[98:101]
	v_mfma_f32_16x16x32_bf16 v[90:93], v[170:173], v[186:189], v[90:93]
	v_mfma_f32_16x16x32_bf16 v[82:85], v[162:165], v[202:205], v[82:85]
	v_mfma_f32_16x16x32_bf16 v[74:77], v[170:173], v[202:205], v[74:77]
	v_mfma_f32_16x16x32_bf16 v[70:73], v[162:165], v[220:223], v[70:73]
	v_mfma_f32_16x16x32_bf16 v[66:69], v[170:173], v[220:223], v[66:69]
	v_mfma_f32_16x16x32_bf16 v[114:117], v[166:169], v[182:185], v[114:117]
	v_mfma_f32_16x16x32_bf16 v[106:109], v[174:177], v[182:185], v[106:109]
	v_mfma_f32_16x16x32_bf16 v[98:101], v[166:169], v[190:193], v[98:101]
	v_mfma_f32_16x16x32_bf16 v[90:93], v[174:177], v[190:193], v[90:93]
	v_mfma_f32_16x16x32_bf16 v[82:85], v[166:169], v[206:209], v[82:85]
	v_mfma_f32_16x16x32_bf16 v[74:77], v[174:177], v[206:209], v[74:77]
	v_mfma_f32_16x16x32_bf16 v[70:73], v[166:169], v[224:227], v[70:73]
	v_mfma_f32_16x16x32_bf16 v[66:69], v[174:177], v[224:227], v[66:69]
	s_setprio 0
	s_barrier
	s_add_i32 s42, s45, s54
	v_lshl_add_u64 v[140:141], v[140:141], 0, s[84:85]
	s_mov_b32 m0, s42
	ds_read_b128 v[178:181], v145 offset:49152
	ds_read_b128 v[182:185], v145 offset:50176
	ds_read_b128 v[186:189], v145 offset:51200
	ds_read_b128 v[190:193], v145 offset:52224
	ds_read_b128 v[202:205], v145 offset:53248
	ds_read_b128 v[206:209], v145 offset:54272
	ds_read_b128 v[220:223], v145 offset:55296
	ds_read_b128 v[224:227], v145 offset:56320
	global_load_lds_dwordx4 v[140:141], off
	v_lshl_add_u64 v[140:141], v[194:195], 0, s[84:85]
	s_add_i32 m0, s42, 0x2000
	s_add_i32 s42, s73, s54
	global_load_lds_dwordx4 v[140:141], off
	v_lshl_add_u64 v[140:141], v[198:199], 0, s[84:85]
	s_mov_b32 m0, s42
	s_nop 0
	global_load_lds_dwordx4 v[140:141], off
	v_lshl_add_u64 v[140:141], v[200:201], 0, s[84:85]
	s_add_i32 m0, s42, 0x2000
	s_nop 0
	global_load_lds_dwordx4 v[140:141], off
	v_lshl_add_u64 v[140:141], v[210:211], 0, s[84:85]
	s_mov_b32 m0, s64
	s_nop 0
	global_load_lds_dwordx4 v[140:141], off
	v_lshl_add_u64 v[140:141], v[212:213], 0, s[84:85]
	s_mov_b32 m0, s65
	s_nop 0
	global_load_lds_dwordx4 v[140:141], off
	s_waitcnt vmcnt(8)
	s_waitcnt lgkmcnt(0)
	s_barrier
	s_setprio 1
	s_waitcnt lgkmcnt(0)
	v_mfma_f32_16x16x32_bf16 v[62:65], v[146:149], v[178:181], v[62:65]
	v_mfma_f32_16x16x32_bf16 v[58:61], v[154:157], v[178:181], v[58:61]
	v_mfma_f32_16x16x32_bf16 v[54:57], v[146:149], v[186:189], v[54:57]
	v_mfma_f32_16x16x32_bf16 v[46:49], v[154:157], v[186:189], v[46:49]
	v_mfma_f32_16x16x32_bf16 v[38:41], v[146:149], v[202:205], v[38:41]
	v_mfma_f32_16x16x32_bf16 v[30:33], v[154:157], v[202:205], v[30:33]
	v_mfma_f32_16x16x32_bf16 v[22:25], v[146:149], v[220:223], v[22:25]
	v_mfma_f32_16x16x32_bf16 v[14:17], v[154:157], v[220:223], v[14:17]
	v_mfma_f32_16x16x32_bf16 v[62:65], v[150:153], v[182:185], v[62:65]
	v_mfma_f32_16x16x32_bf16 v[58:61], v[158:161], v[182:185], v[58:61]
	v_mfma_f32_16x16x32_bf16 v[54:57], v[150:153], v[190:193], v[54:57]
	v_mfma_f32_16x16x32_bf16 v[46:49], v[158:161], v[190:193], v[46:49]
	v_mfma_f32_16x16x32_bf16 v[38:41], v[150:153], v[206:209], v[38:41]
	v_mfma_f32_16x16x32_bf16 v[30:33], v[158:161], v[206:209], v[30:33]
	v_mfma_f32_16x16x32_bf16 v[22:25], v[150:153], v[224:227], v[22:25]
	v_mfma_f32_16x16x32_bf16 v[14:17], v[158:161], v[224:227], v[14:17]
	v_mfma_f32_16x16x32_bf16 v[50:53], v[162:165], v[178:181], v[50:53]
	v_mfma_f32_16x16x32_bf16 v[42:45], v[170:173], v[178:181], v[42:45]
	v_mfma_f32_16x16x32_bf16 v[34:37], v[162:165], v[186:189], v[34:37]
	v_mfma_f32_16x16x32_bf16 v[26:29], v[170:173], v[186:189], v[26:29]
	v_mfma_f32_16x16x32_bf16 v[18:21], v[162:165], v[202:205], v[18:21]
	v_mfma_f32_16x16x32_bf16 v[10:13], v[170:173], v[202:205], v[10:13]
	v_mfma_f32_16x16x32_bf16 v[6:9], v[162:165], v[220:223], v[6:9]
	v_mfma_f32_16x16x32_bf16 v[2:5], v[170:173], v[220:223], v[2:5]
	v_mfma_f32_16x16x32_bf16 v[50:53], v[166:169], v[182:185], v[50:53]
	v_mfma_f32_16x16x32_bf16 v[42:45], v[174:177], v[182:185], v[42:45]
	v_mfma_f32_16x16x32_bf16 v[34:37], v[166:169], v[190:193], v[34:37]
	v_mfma_f32_16x16x32_bf16 v[26:29], v[174:177], v[190:193], v[26:29]
	v_mfma_f32_16x16x32_bf16 v[18:21], v[166:169], v[206:209], v[18:21]
	v_mfma_f32_16x16x32_bf16 v[10:13], v[174:177], v[206:209], v[10:13]
	v_mfma_f32_16x16x32_bf16 v[6:9], v[166:169], v[224:227], v[6:9]
	v_mfma_f32_16x16x32_bf16 v[2:5], v[174:177], v[224:227], v[2:5]
	s_setprio 0
	s_barrier
	s_add_u32 vcc_lo, vcc_lo, 0x100
	s_addc_u32 vcc_hi, vcc_hi, 0
	s_add_u32 s82, s82, 0x100
	s_addc_u32 s83, s83, 0
	s_cmp_ge_u32 s72, s66
	s_mov_b32 s42, s72
	s_cbranch_scc0 .LBB0_308

.LBB0_351:
	s_add_u32 s8, s76, 0x80
	s_addc_u32 s9, s77, 0
	s_add_u32 s59, s36, 0x100
	s_addc_u32 s60, s37, 0
	s_mov_b32 s36, 0
	s_add_i32 s61, s36, 2
	s_add_u32 s45, s8, 0x80
	s_addc_u32 s37, s9, 0
	s_add_i32 s64, 0, 0x10000
	s_cmp_eq_u32 s48, s36
	s_cselect_b32 s37, s39, s37
	s_cselect_b32 s36, s38, s45
	s_cselect_b32 s63, s41, s60
	s_cselect_b32 s62, s40, s59
	s_add_i32 s45, 0, 0x14000
	v_add_u32_e32 v158, s64, v148
	v_add_u32_e32 v174, s45, v148
	ds_read_b128 v[144:147], v158
	ds_read_b128 v[150:153], v158 offset:1024
	ds_read_b128 v[154:157], v158 offset:2048
	ds_read_b128 v[158:161], v158 offset:3072
	ds_read_b128 v[162:165], v174
	ds_read_b128 v[166:169], v174 offset:1024
	ds_read_b128 v[170:173], v174 offset:2048
	ds_read_b128 v[174:177], v174 offset:3072
	v_lshl_add_u64 v[194:195], s[8:9], 0, v[140:141]
	s_add_i32 m0, s82, 0xc000
	ds_read_b128 v[178:181], v149
	ds_read_b128 v[182:185], v149 offset:1024
	ds_read_b128 v[186:189], v149 offset:2048
	ds_read_b128 v[190:193], v149 offset:3072
	ds_read_b128 v[202:205], v149 offset:4096
	ds_read_b128 v[206:209], v149 offset:5120
	ds_read_b128 v[220:223], v149 offset:6144
	ds_read_b128 v[224:227], v149 offset:7168
	global_load_lds_dwordx4 v[194:195], off
	v_lshl_add_u64 v[194:195], s[8:9], 0, v[142:143]
	s_add_i32 m0, s82, 0xe000
	s_nop 0
	global_load_lds_dwordx4 v[194:195], off
	s_waitcnt vmcnt(8)
	s_waitcnt lgkmcnt(0)
	s_barrier
	s_setprio 1
	s_waitcnt lgkmcnt(0)
	v_mfma_f32_16x16x32_bf16 v[126:129], v[144:147], v[178:181], 0
	v_mfma_f32_16x16x32_bf16 v[122:125], v[154:157], v[178:181], 0
	v_mfma_f32_16x16x32_bf16 v[110:113], v[144:147], v[186:189], 0
	v_mfma_f32_16x16x32_bf16 v[106:109], v[154:157], v[186:189], 0
	v_mfma_f32_16x16x32_bf16 v[94:97], v[144:147], v[202:205], 0
	v_mfma_f32_16x16x32_bf16 v[90:93], v[154:157], v[202:205], 0
	v_mfma_f32_16x16x32_bf16 v[78:81], v[144:147], v[220:223], 0
	v_mfma_f32_16x16x32_bf16 v[74:77], v[154:157], v[220:223], 0
	v_mfma_f32_16x16x32_bf16 v[126:129], v[150:153], v[182:185], v[126:129]
	v_mfma_f32_16x16x32_bf16 v[122:125], v[158:161], v[182:185], v[122:125]
	v_mfma_f32_16x16x32_bf16 v[110:113], v[150:153], v[190:193], v[110:113]
	v_mfma_f32_16x16x32_bf16 v[106:109], v[158:161], v[190:193], v[106:109]
	v_mfma_f32_16x16x32_bf16 v[94:97], v[150:153], v[206:209], v[94:97]
	v_mfma_f32_16x16x32_bf16 v[90:93], v[158:161], v[206:209], v[90:93]
	v_mfma_f32_16x16x32_bf16 v[78:81], v[150:153], v[224:227], v[78:81]
	v_mfma_f32_16x16x32_bf16 v[74:77], v[158:161], v[224:227], v[74:77]
	v_mfma_f32_16x16x32_bf16 v[118:121], v[162:165], v[178:181], 0
	v_mfma_f32_16x16x32_bf16 v[114:117], v[170:173], v[178:181], 0
	v_mfma_f32_16x16x32_bf16 v[102:105], v[162:165], v[186:189], 0
	v_mfma_f32_16x16x32_bf16 v[98:101], v[170:173], v[186:189], 0
	v_mfma_f32_16x16x32_bf16 v[86:89], v[162:165], v[202:205], 0
	v_mfma_f32_16x16x32_bf16 v[82:85], v[170:173], v[202:205], 0
	v_mfma_f32_16x16x32_bf16 v[70:73], v[162:165], v[220:223], 0
	v_mfma_f32_16x16x32_bf16 v[66:69], v[170:173], v[220:223], 0
	v_mfma_f32_16x16x32_bf16 v[118:121], v[166:169], v[182:185], v[118:121]
	v_mfma_f32_16x16x32_bf16 v[114:117], v[174:177], v[182:185], v[114:117]
	v_mfma_f32_16x16x32_bf16 v[102:105], v[166:169], v[190:193], v[102:105]
	v_mfma_f32_16x16x32_bf16 v[98:101], v[174:177], v[190:193], v[98:101]
	v_mfma_f32_16x16x32_bf16 v[86:89], v[166:169], v[206:209], v[86:89]
	v_mfma_f32_16x16x32_bf16 v[82:85], v[174:177], v[206:209], v[82:85]
	v_mfma_f32_16x16x32_bf16 v[70:73], v[166:169], v[224:227], v[70:73]
	v_mfma_f32_16x16x32_bf16 v[66:69], v[174:177], v[224:227], v[66:69]
	s_setprio 0
	s_barrier
	s_add_i32 s64, s64, s79
	v_lshl_add_u64 v[194:195], s[62:63], 0, v[132:133]
	s_mov_b32 m0, s64
	ds_read_b128 v[178:181], v149 offset:16384
	ds_read_b128 v[182:185], v149 offset:17408
	ds_read_b128 v[186:189], v149 offset:18432
	ds_read_b128 v[190:193], v149 offset:19456
	ds_read_b128 v[202:205], v149 offset:20480
	ds_read_b128 v[206:209], v149 offset:21504
	ds_read_b128 v[220:223], v149 offset:22528
	ds_read_b128 v[224:227], v149 offset:23552
	global_load_lds_dwordx4 v[194:195], off
	s_add_i32 m0, s64, 0x2000
	v_lshl_add_u64 v[198:199], s[62:63], 0, v[136:137]
	s_add_u32 s62, s62, s80
	s_addc_u32 s63, s63, 0
	s_add_i32 s45, s45, s79
	global_load_lds_dwordx4 v[198:199], off
	v_lshl_add_u64 v[200:201], s[62:63], 0, v[132:133]
	s_mov_b32 m0, s45
	v_lshl_add_u64 v[210:211], s[62:63], 0, v[136:137]
	global_load_lds_dwordx4 v[200:201], off
	s_add_i32 m0, s45, 0x2000
	v_lshl_add_u64 v[212:213], s[36:37], 0, v[130:131]
	global_load_lds_dwordx4 v[210:211], off
	s_mov_b32 m0, s82
	v_lshl_add_u64 v[214:215], s[36:37], 0, v[134:135]
	global_load_lds_dwordx4 v[212:213], off
	s_mov_b32 m0, s83
	s_nop 0
	global_load_lds_dwordx4 v[214:215], off
	s_waitcnt vmcnt(8)
	s_waitcnt lgkmcnt(0)
	s_barrier
	s_setprio 1
	s_waitcnt lgkmcnt(0)
	v_mfma_f32_16x16x32_bf16 v[62:65], v[144:147], v[178:181], 0
	v_mfma_f32_16x16x32_bf16 v[58:61], v[154:157], v[178:181], 0
	v_mfma_f32_16x16x32_bf16 v[46:49], v[144:147], v[186:189], 0
	v_mfma_f32_16x16x32_bf16 v[42:45], v[154:157], v[186:189], 0
	v_mfma_f32_16x16x32_bf16 v[30:33], v[144:147], v[202:205], 0
	v_mfma_f32_16x16x32_bf16 v[26:29], v[154:157], v[202:205], 0
	v_mfma_f32_16x16x32_bf16 v[14:17], v[144:147], v[220:223], 0
	v_mfma_f32_16x16x32_bf16 v[10:13], v[154:157], v[220:223], 0
	v_mfma_f32_16x16x32_bf16 v[62:65], v[150:153], v[182:185], v[62:65]
	v_mfma_f32_16x16x32_bf16 v[58:61], v[158:161], v[182:185], v[58:61]
	v_mfma_f32_16x16x32_bf16 v[46:49], v[150:153], v[190:193], v[46:49]
	v_mfma_f32_16x16x32_bf16 v[42:45], v[158:161], v[190:193], v[42:45]
	v_mfma_f32_16x16x32_bf16 v[30:33], v[150:153], v[206:209], v[30:33]
	v_mfma_f32_16x16x32_bf16 v[26:29], v[158:161], v[206:209], v[26:29]
	v_mfma_f32_16x16x32_bf16 v[14:17], v[150:153], v[224:227], v[14:17]
	v_mfma_f32_16x16x32_bf16 v[10:13], v[158:161], v[224:227], v[10:13]
	v_mfma_f32_16x16x32_bf16 v[54:57], v[162:165], v[178:181], 0
	v_mfma_f32_16x16x32_bf16 v[50:53], v[170:173], v[178:181], 0
	v_mfma_f32_16x16x32_bf16 v[38:41], v[162:165], v[186:189], 0
	v_mfma_f32_16x16x32_bf16 v[34:37], v[170:173], v[186:189], 0
	v_mfma_f32_16x16x32_bf16 v[22:25], v[162:165], v[202:205], 0
	v_mfma_f32_16x16x32_bf16 v[18:21], v[170:173], v[202:205], 0
	v_mfma_f32_16x16x32_bf16 v[6:9], v[162:165], v[220:223], 0
	v_mfma_f32_16x16x32_bf16 v[2:5], v[170:173], v[220:223], 0
	v_mfma_f32_16x16x32_bf16 v[54:57], v[166:169], v[182:185], v[54:57]
	v_mfma_f32_16x16x32_bf16 v[50:53], v[174:177], v[182:185], v[50:53]
	v_mfma_f32_16x16x32_bf16 v[38:41], v[166:169], v[190:193], v[38:41]
	v_mfma_f32_16x16x32_bf16 v[34:37], v[174:177], v[190:193], v[34:37]
	v_mfma_f32_16x16x32_bf16 v[22:25], v[166:169], v[206:209], v[22:25]
	v_mfma_f32_16x16x32_bf16 v[18:21], v[174:177], v[206:209], v[18:21]
	v_mfma_f32_16x16x32_bf16 v[6:9], v[166:169], v[224:227], v[6:9]
	v_mfma_f32_16x16x32_bf16 v[2:5], v[174:177], v[224:227], v[2:5]
	s_setprio 0
	s_barrier
	s_add_i32 s45, 0, 0x18000
	s_add_i32 s62, 0, 0x1c000
	v_add_u32_e32 v158, s45, v148
	v_add_u32_e32 v174, s62, v148
	ds_read_b128 v[144:147], v158
	ds_read_b128 v[150:153], v158 offset:1024
	ds_read_b128 v[154:157], v158 offset:2048
	ds_read_b128 v[158:161], v158 offset:3072
	ds_read_b128 v[162:165], v174
	ds_read_b128 v[166:169], v174 offset:1024
	ds_read_b128 v[170:173], v174 offset:2048
	ds_read_b128 v[174:177], v174 offset:3072
	s_add_u32 s36, s36, s80
	s_addc_u32 s37, s37, 0
	s_mov_b32 m0, s86
	v_lshl_add_u64 v[216:217], s[36:37], 0, v[130:131]
	ds_read_b128 v[178:181], v149 offset:32768
	ds_read_b128 v[182:185], v149 offset:33792
	ds_read_b128 v[186:189], v149 offset:34816
	ds_read_b128 v[190:193], v149 offset:35840
	ds_read_b128 v[202:205], v149 offset:36864
	ds_read_b128 v[206:209], v149 offset:37888
	ds_read_b128 v[220:223], v149 offset:38912
	ds_read_b128 v[224:227], v149 offset:39936
	global_load_lds_dwordx4 v[216:217], off
	v_lshl_add_u64 v[216:217], s[36:37], 0, v[134:135]
	s_mov_b32 m0, s87
	s_nop 0
	global_load_lds_dwordx4 v[216:217], off
	s_waitcnt vmcnt(8)
	s_waitcnt lgkmcnt(0)
	s_barrier
	s_setprio 1
	s_waitcnt lgkmcnt(0)
	v_mfma_f32_16x16x32_bf16 v[126:129], v[144:147], v[178:181], v[126:129]
	v_mfma_f32_16x16x32_bf16 v[122:125], v[154:157], v[178:181], v[122:125]
	v_mfma_f32_16x16x32_bf16 v[110:113], v[144:147], v[186:189], v[110:113]
	v_mfma_f32_16x16x32_bf16 v[106:109], v[154:157], v[186:189], v[106:109]
	v_mfma_f32_16x16x32_bf16 v[94:97], v[144:147], v[202:205], v[94:97]
	v_mfma_f32_16x16x32_bf16 v[90:93], v[154:157], v[202:205], v[90:93]
	v_mfma_f32_16x16x32_bf16 v[78:81], v[144:147], v[220:223], v[78:81]
	v_mfma_f32_16x16x32_bf16 v[74:77], v[154:157], v[220:223], v[74:77]
	v_mfma_f32_16x16x32_bf16 v[126:129], v[150:153], v[182:185], v[126:129]
	v_mfma_f32_16x16x32_bf16 v[122:125], v[158:161], v[182:185], v[122:125]
	v_mfma_f32_16x16x32_bf16 v[110:113], v[150:153], v[190:193], v[110:113]
	v_mfma_f32_16x16x32_bf16 v[106:109], v[158:161], v[190:193], v[106:109]
	v_mfma_f32_16x16x32_bf16 v[94:97], v[150:153], v[206:209], v[94:97]
	v_mfma_f32_16x16x32_bf16 v[90:93], v[158:161], v[206:209], v[90:93]
	v_mfma_f32_16x16x32_bf16 v[78:81], v[150:153], v[224:227], v[78:81]
	v_mfma_f32_16x16x32_bf16 v[74:77], v[158:161], v[224:227], v[74:77]
	v_mfma_f32_16x16x32_bf16 v[118:121], v[162:165], v[178:181], v[118:121]
	v_mfma_f32_16x16x32_bf16 v[114:117], v[170:173], v[178:181], v[114:117]
	v_mfma_f32_16x16x32_bf16 v[102:105], v[162:165], v[186:189], v[102:105]
	v_mfma_f32_16x16x32_bf16 v[98:101], v[170:173], v[186:189], v[98:101]
	v_mfma_f32_16x16x32_bf16 v[86:89], v[162:165], v[202:205], v[86:89]
	v_mfma_f32_16x16x32_bf16 v[82:85], v[170:173], v[202:205], v[82:85]
	v_mfma_f32_16x16x32_bf16 v[70:73], v[162:165], v[220:223], v[70:73]
	v_mfma_f32_16x16x32_bf16 v[66:69], v[170:173], v[220:223], v[66:69]
	v_mfma_f32_16x16x32_bf16 v[118:121], v[166:169], v[182:185], v[118:121]
	v_mfma_f32_16x16x32_bf16 v[114:117], v[174:177], v[182:185], v[114:117]
	v_mfma_f32_16x16x32_bf16 v[102:105], v[166:169], v[190:193], v[102:105]
	v_mfma_f32_16x16x32_bf16 v[98:101], v[174:177], v[190:193], v[98:101]
	v_mfma_f32_16x16x32_bf16 v[86:89], v[166:169], v[206:209], v[86:89]
	v_mfma_f32_16x16x32_bf16 v[82:85], v[174:177], v[206:209], v[82:85]
	v_mfma_f32_16x16x32_bf16 v[70:73], v[166:169], v[224:227], v[70:73]
	v_mfma_f32_16x16x32_bf16 v[66:69], v[174:177], v[224:227], v[66:69]
	s_setprio 0
	s_barrier
	s_add_i32 s36, s45, s79
	v_lshl_add_u64 v[194:195], v[194:195], 0, s[84:85]
	s_mov_b32 m0, s36
	ds_read_b128 v[178:181], v149 offset:49152
	ds_read_b128 v[182:185], v149 offset:50176
	ds_read_b128 v[186:189], v149 offset:51200
	ds_read_b128 v[190:193], v149 offset:52224
	ds_read_b128 v[202:205], v149 offset:53248
	ds_read_b128 v[206:209], v149 offset:54272
	ds_read_b128 v[220:223], v149 offset:55296
	ds_read_b128 v[224:227], v149 offset:56320
	global_load_lds_dwordx4 v[194:195], off
	v_lshl_add_u64 v[194:195], v[198:199], 0, s[84:85]
	s_add_i32 m0, s36, 0x2000
	s_add_i32 s36, s62, s79
	global_load_lds_dwordx4 v[194:195], off
	v_lshl_add_u64 v[194:195], v[200:201], 0, s[84:85]
	s_mov_b32 m0, s36
	s_nop 0
	global_load_lds_dwordx4 v[194:195], off
	v_lshl_add_u64 v[194:195], v[210:211], 0, s[84:85]
	s_add_i32 m0, s36, 0x2000
	s_nop 0
	global_load_lds_dwordx4 v[194:195], off
	v_lshl_add_u64 v[194:195], v[212:213], 0, s[84:85]
	s_mov_b32 m0, s46
	s_nop 0
	global_load_lds_dwordx4 v[194:195], off
	v_lshl_add_u64 v[194:195], v[214:215], 0, s[84:85]
	s_mov_b32 m0, s47
	s_nop 0
	global_load_lds_dwordx4 v[194:195], off
	s_waitcnt vmcnt(8)
	s_waitcnt lgkmcnt(0)
	s_barrier
	s_setprio 1
	s_waitcnt lgkmcnt(0)
	v_mfma_f32_16x16x32_bf16 v[62:65], v[144:147], v[178:181], v[62:65]
	v_mfma_f32_16x16x32_bf16 v[58:61], v[154:157], v[178:181], v[58:61]
	v_mfma_f32_16x16x32_bf16 v[46:49], v[144:147], v[186:189], v[46:49]
	v_mfma_f32_16x16x32_bf16 v[42:45], v[154:157], v[186:189], v[42:45]
	v_mfma_f32_16x16x32_bf16 v[30:33], v[144:147], v[202:205], v[30:33]
	v_mfma_f32_16x16x32_bf16 v[26:29], v[154:157], v[202:205], v[26:29]
	v_mfma_f32_16x16x32_bf16 v[14:17], v[144:147], v[220:223], v[14:17]
	v_mfma_f32_16x16x32_bf16 v[10:13], v[154:157], v[220:223], v[10:13]
	v_mfma_f32_16x16x32_bf16 v[62:65], v[150:153], v[182:185], v[62:65]
	v_mfma_f32_16x16x32_bf16 v[58:61], v[158:161], v[182:185], v[58:61]
	v_mfma_f32_16x16x32_bf16 v[46:49], v[150:153], v[190:193], v[46:49]
	v_mfma_f32_16x16x32_bf16 v[42:45], v[158:161], v[190:193], v[42:45]
	v_mfma_f32_16x16x32_bf16 v[30:33], v[150:153], v[206:209], v[30:33]
	v_mfma_f32_16x16x32_bf16 v[26:29], v[158:161], v[206:209], v[26:29]
	v_mfma_f32_16x16x32_bf16 v[14:17], v[150:153], v[224:227], v[14:17]
	v_mfma_f32_16x16x32_bf16 v[10:13], v[158:161], v[224:227], v[10:13]
	v_mfma_f32_16x16x32_bf16 v[54:57], v[162:165], v[178:181], v[54:57]
	v_mfma_f32_16x16x32_bf16 v[50:53], v[170:173], v[178:181], v[50:53]
	v_mfma_f32_16x16x32_bf16 v[38:41], v[162:165], v[186:189], v[38:41]
	v_mfma_f32_16x16x32_bf16 v[34:37], v[170:173], v[186:189], v[34:37]
	v_mfma_f32_16x16x32_bf16 v[22:25], v[162:165], v[202:205], v[22:25]
	v_mfma_f32_16x16x32_bf16 v[18:21], v[170:173], v[202:205], v[18:21]
	v_mfma_f32_16x16x32_bf16 v[6:9], v[162:165], v[220:223], v[6:9]
	v_mfma_f32_16x16x32_bf16 v[2:5], v[170:173], v[220:223], v[2:5]
	v_mfma_f32_16x16x32_bf16 v[54:57], v[166:169], v[182:185], v[54:57]
	v_mfma_f32_16x16x32_bf16 v[50:53], v[174:177], v[182:185], v[50:53]
	v_mfma_f32_16x16x32_bf16 v[38:41], v[166:169], v[190:193], v[38:41]
	v_mfma_f32_16x16x32_bf16 v[34:37], v[174:177], v[190:193], v[34:37]
	v_mfma_f32_16x16x32_bf16 v[22:25], v[166:169], v[206:209], v[22:25]
	v_mfma_f32_16x16x32_bf16 v[18:21], v[174:177], v[206:209], v[18:21]
	v_mfma_f32_16x16x32_bf16 v[6:9], v[166:169], v[224:227], v[6:9]
	v_mfma_f32_16x16x32_bf16 v[2:5], v[174:177], v[224:227], v[2:5]
	s_setprio 0
	s_barrier
	s_add_u32 s8, s8, 0x100
	s_addc_u32 s9, s9, 0
	s_add_u32 s59, s59, 0x100
	s_addc_u32 s60, s60, 0
	s_cmp_ge_u32 s61, s90
	s_mov_b32 s36, s61
	s_cbranch_scc1 .Lpeel_exit_vt
.LBB0_352:
	s_add_i32 s61, s36, 2
	s_add_u32 s45, s8, 0x80
	s_addc_u32 s37, s9, 0
	s_add_i32 s64, 0, 0x10000
	s_cmp_eq_u32 s48, s36
	s_cselect_b32 s37, s39, s37
	s_cselect_b32 s36, s38, s45
	s_cselect_b32 s63, s41, s60
	s_cselect_b32 s62, s40, s59
	s_add_i32 s45, 0, 0x14000
	v_add_u32_e32 v158, s64, v148
	v_add_u32_e32 v174, s45, v148
	ds_read_b128 v[144:147], v158
	ds_read_b128 v[150:153], v158 offset:1024
	ds_read_b128 v[154:157], v158 offset:2048
	ds_read_b128 v[158:161], v158 offset:3072
	ds_read_b128 v[162:165], v174
	ds_read_b128 v[166:169], v174 offset:1024
	ds_read_b128 v[170:173], v174 offset:2048
	ds_read_b128 v[174:177], v174 offset:3072
	v_lshl_add_u64 v[194:195], s[8:9], 0, v[140:141]
	s_add_i32 m0, s82, 0xc000
	ds_read_b128 v[178:181], v149
	ds_read_b128 v[182:185], v149 offset:1024
	ds_read_b128 v[186:189], v149 offset:2048
	ds_read_b128 v[190:193], v149 offset:3072
	ds_read_b128 v[202:205], v149 offset:4096
	ds_read_b128 v[206:209], v149 offset:5120
	ds_read_b128 v[220:223], v149 offset:6144
	ds_read_b128 v[224:227], v149 offset:7168
	global_load_lds_dwordx4 v[194:195], off
	v_lshl_add_u64 v[194:195], s[8:9], 0, v[142:143]
	s_add_i32 m0, s82, 0xe000
	s_nop 0
	global_load_lds_dwordx4 v[194:195], off
	s_waitcnt vmcnt(8)
	s_waitcnt lgkmcnt(0)
	s_barrier
	s_setprio 1
	s_waitcnt lgkmcnt(0)
	v_mfma_f32_16x16x32_bf16 v[126:129], v[144:147], v[178:181], v[126:129]
	v_mfma_f32_16x16x32_bf16 v[122:125], v[154:157], v[178:181], v[122:125]
	v_mfma_f32_16x16x32_bf16 v[110:113], v[144:147], v[186:189], v[110:113]
	v_mfma_f32_16x16x32_bf16 v[106:109], v[154:157], v[186:189], v[106:109]
	v_mfma_f32_16x16x32_bf16 v[94:97], v[144:147], v[202:205], v[94:97]
	v_mfma_f32_16x16x32_bf16 v[90:93], v[154:157], v[202:205], v[90:93]
	v_mfma_f32_16x16x32_bf16 v[78:81], v[144:147], v[220:223], v[78:81]
	v_mfma_f32_16x16x32_bf16 v[74:77], v[154:157], v[220:223], v[74:77]
	v_mfma_f32_16x16x32_bf16 v[126:129], v[150:153], v[182:185], v[126:129]
	v_mfma_f32_16x16x32_bf16 v[122:125], v[158:161], v[182:185], v[122:125]
	v_mfma_f32_16x16x32_bf16 v[110:113], v[150:153], v[190:193], v[110:113]
	v_mfma_f32_16x16x32_bf16 v[106:109], v[158:161], v[190:193], v[106:109]
	v_mfma_f32_16x16x32_bf16 v[94:97], v[150:153], v[206:209], v[94:97]
	v_mfma_f32_16x16x32_bf16 v[90:93], v[158:161], v[206:209], v[90:93]
	v_mfma_f32_16x16x32_bf16 v[78:81], v[150:153], v[224:227], v[78:81]
	v_mfma_f32_16x16x32_bf16 v[74:77], v[158:161], v[224:227], v[74:77]
	v_mfma_f32_16x16x32_bf16 v[118:121], v[162:165], v[178:181], v[118:121]
	v_mfma_f32_16x16x32_bf16 v[114:117], v[170:173], v[178:181], v[114:117]
	v_mfma_f32_16x16x32_bf16 v[102:105], v[162:165], v[186:189], v[102:105]
	v_mfma_f32_16x16x32_bf16 v[98:101], v[170:173], v[186:189], v[98:101]
	v_mfma_f32_16x16x32_bf16 v[86:89], v[162:165], v[202:205], v[86:89]
	v_mfma_f32_16x16x32_bf16 v[82:85], v[170:173], v[202:205], v[82:85]
	v_mfma_f32_16x16x32_bf16 v[70:73], v[162:165], v[220:223], v[70:73]
	v_mfma_f32_16x16x32_bf16 v[66:69], v[170:173], v[220:223], v[66:69]
	v_mfma_f32_16x16x32_bf16 v[118:121], v[166:169], v[182:185], v[118:121]
	v_mfma_f32_16x16x32_bf16 v[114:117], v[174:177], v[182:185], v[114:117]
	v_mfma_f32_16x16x32_bf16 v[102:105], v[166:169], v[190:193], v[102:105]
	v_mfma_f32_16x16x32_bf16 v[98:101], v[174:177], v[190:193], v[98:101]
	v_mfma_f32_16x16x32_bf16 v[86:89], v[166:169], v[206:209], v[86:89]
	v_mfma_f32_16x16x32_bf16 v[82:85], v[174:177], v[206:209], v[82:85]
	v_mfma_f32_16x16x32_bf16 v[70:73], v[166:169], v[224:227], v[70:73]
	v_mfma_f32_16x16x32_bf16 v[66:69], v[174:177], v[224:227], v[66:69]
	s_setprio 0
	s_barrier
	s_add_i32 s64, s64, s79
	v_lshl_add_u64 v[194:195], s[62:63], 0, v[132:133]
	s_mov_b32 m0, s64
	ds_read_b128 v[178:181], v149 offset:16384
	ds_read_b128 v[182:185], v149 offset:17408
	ds_read_b128 v[186:189], v149 offset:18432
	ds_read_b128 v[190:193], v149 offset:19456
	ds_read_b128 v[202:205], v149 offset:20480
	ds_read_b128 v[206:209], v149 offset:21504
	ds_read_b128 v[220:223], v149 offset:22528
	ds_read_b128 v[224:227], v149 offset:23552
	global_load_lds_dwordx4 v[194:195], off
	s_add_i32 m0, s64, 0x2000
	v_lshl_add_u64 v[198:199], s[62:63], 0, v[136:137]
	s_add_u32 s62, s62, s80
	s_addc_u32 s63, s63, 0
	s_add_i32 s45, s45, s79
	global_load_lds_dwordx4 v[198:199], off
	v_lshl_add_u64 v[200:201], s[62:63], 0, v[132:133]
	s_mov_b32 m0, s45
	v_lshl_add_u64 v[210:211], s[62:63], 0, v[136:137]
	global_load_lds_dwordx4 v[200:201], off
	s_add_i32 m0, s45, 0x2000
	v_lshl_add_u64 v[212:213], s[36:37], 0, v[130:131]
	global_load_lds_dwordx4 v[210:211], off
	s_mov_b32 m0, s82
	v_lshl_add_u64 v[214:215], s[36:37], 0, v[134:135]
	global_load_lds_dwordx4 v[212:213], off
	s_mov_b32 m0, s83
	s_nop 0
	global_load_lds_dwordx4 v[214:215], off
	s_waitcnt vmcnt(8)
	s_waitcnt lgkmcnt(0)
	s_barrier
	s_setprio 1
	s_waitcnt lgkmcnt(0)
	v_mfma_f32_16x16x32_bf16 v[62:65], v[144:147], v[178:181], v[62:65]
	v_mfma_f32_16x16x32_bf16 v[58:61], v[154:157], v[178:181], v[58:61]
	v_mfma_f32_16x16x32_bf16 v[46:49], v[144:147], v[186:189], v[46:49]
	v_mfma_f32_16x16x32_bf16 v[42:45], v[154:157], v[186:189], v[42:45]
	v_mfma_f32_16x16x32_bf16 v[30:33], v[144:147], v[202:205], v[30:33]
	v_mfma_f32_16x16x32_bf16 v[26:29], v[154:157], v[202:205], v[26:29]
	v_mfma_f32_16x16x32_bf16 v[14:17], v[144:147], v[220:223], v[14:17]
	v_mfma_f32_16x16x32_bf16 v[10:13], v[154:157], v[220:223], v[10:13]
	v_mfma_f32_16x16x32_bf16 v[62:65], v[150:153], v[182:185], v[62:65]
	v_mfma_f32_16x16x32_bf16 v[58:61], v[158:161], v[182:185], v[58:61]
	v_mfma_f32_16x16x32_bf16 v[46:49], v[150:153], v[190:193], v[46:49]
	v_mfma_f32_16x16x32_bf16 v[42:45], v[158:161], v[190:193], v[42:45]
	v_mfma_f32_16x16x32_bf16 v[30:33], v[150:153], v[206:209], v[30:33]
	v_mfma_f32_16x16x32_bf16 v[26:29], v[158:161], v[206:209], v[26:29]
	v_mfma_f32_16x16x32_bf16 v[14:17], v[150:153], v[224:227], v[14:17]
	v_mfma_f32_16x16x32_bf16 v[10:13], v[158:161], v[224:227], v[10:13]
	v_mfma_f32_16x16x32_bf16 v[54:57], v[162:165], v[178:181], v[54:57]
	v_mfma_f32_16x16x32_bf16 v[50:53], v[170:173], v[178:181], v[50:53]
	v_mfma_f32_16x16x32_bf16 v[38:41], v[162:165], v[186:189], v[38:41]
	v_mfma_f32_16x16x32_bf16 v[34:37], v[170:173], v[186:189], v[34:37]
	v_mfma_f32_16x16x32_bf16 v[22:25], v[162:165], v[202:205], v[22:25]
	v_mfma_f32_16x16x32_bf16 v[18:21], v[170:173], v[202:205], v[18:21]
	v_mfma_f32_16x16x32_bf16 v[6:9], v[162:165], v[220:223], v[6:9]
	v_mfma_f32_16x16x32_bf16 v[2:5], v[170:173], v[220:223], v[2:5]
	v_mfma_f32_16x16x32_bf16 v[54:57], v[166:169], v[182:185], v[54:57]
	v_mfma_f32_16x16x32_bf16 v[50:53], v[174:177], v[182:185], v[50:53]
	v_mfma_f32_16x16x32_bf16 v[38:41], v[166:169], v[190:193], v[38:41]
	v_mfma_f32_16x16x32_bf16 v[34:37], v[174:177], v[190:193], v[34:37]
	v_mfma_f32_16x16x32_bf16 v[22:25], v[166:169], v[206:209], v[22:25]
	v_mfma_f32_16x16x32_bf16 v[18:21], v[174:177], v[206:209], v[18:21]
	v_mfma_f32_16x16x32_bf16 v[6:9], v[166:169], v[224:227], v[6:9]
	v_mfma_f32_16x16x32_bf16 v[2:5], v[174:177], v[224:227], v[2:5]
	s_setprio 0
	s_barrier
	s_add_i32 s45, 0, 0x18000
	s_add_i32 s62, 0, 0x1c000
	v_add_u32_e32 v158, s45, v148
	v_add_u32_e32 v174, s62, v148
	ds_read_b128 v[144:147], v158
	ds_read_b128 v[150:153], v158 offset:1024
	ds_read_b128 v[154:157], v158 offset:2048
	ds_read_b128 v[158:161], v158 offset:3072
	ds_read_b128 v[162:165], v174
	ds_read_b128 v[166:169], v174 offset:1024
	ds_read_b128 v[170:173], v174 offset:2048
	ds_read_b128 v[174:177], v174 offset:3072
	s_add_u32 s36, s36, s80
	s_addc_u32 s37, s37, 0
	s_mov_b32 m0, s86
	v_lshl_add_u64 v[216:217], s[36:37], 0, v[130:131]
	ds_read_b128 v[178:181], v149 offset:32768
	ds_read_b128 v[182:185], v149 offset:33792
	ds_read_b128 v[186:189], v149 offset:34816
	ds_read_b128 v[190:193], v149 offset:35840
	ds_read_b128 v[202:205], v149 offset:36864
	ds_read_b128 v[206:209], v149 offset:37888
	ds_read_b128 v[220:223], v149 offset:38912
	ds_read_b128 v[224:227], v149 offset:39936
	global_load_lds_dwordx4 v[216:217], off
	v_lshl_add_u64 v[216:217], s[36:37], 0, v[134:135]
	s_mov_b32 m0, s87
	s_nop 0
	global_load_lds_dwordx4 v[216:217], off
	s_waitcnt vmcnt(8)
	s_waitcnt lgkmcnt(0)
	s_barrier
	s_setprio 1
	s_waitcnt lgkmcnt(0)
	v_mfma_f32_16x16x32_bf16 v[126:129], v[144:147], v[178:181], v[126:129]
	v_mfma_f32_16x16x32_bf16 v[122:125], v[154:157], v[178:181], v[122:125]
	v_mfma_f32_16x16x32_bf16 v[110:113], v[144:147], v[186:189], v[110:113]
	v_mfma_f32_16x16x32_bf16 v[106:109], v[154:157], v[186:189], v[106:109]
	v_mfma_f32_16x16x32_bf16 v[94:97], v[144:147], v[202:205], v[94:97]
	v_mfma_f32_16x16x32_bf16 v[90:93], v[154:157], v[202:205], v[90:93]
	v_mfma_f32_16x16x32_bf16 v[78:81], v[144:147], v[220:223], v[78:81]
	v_mfma_f32_16x16x32_bf16 v[74:77], v[154:157], v[220:223], v[74:77]
	v_mfma_f32_16x16x32_bf16 v[126:129], v[150:153], v[182:185], v[126:129]
	v_mfma_f32_16x16x32_bf16 v[122:125], v[158:161], v[182:185], v[122:125]
	v_mfma_f32_16x16x32_bf16 v[110:113], v[150:153], v[190:193], v[110:113]
	v_mfma_f32_16x16x32_bf16 v[106:109], v[158:161], v[190:193], v[106:109]
	v_mfma_f32_16x16x32_bf16 v[94:97], v[150:153], v[206:209], v[94:97]
	v_mfma_f32_16x16x32_bf16 v[90:93], v[158:161], v[206:209], v[90:93]
	v_mfma_f32_16x16x32_bf16 v[78:81], v[150:153], v[224:227], v[78:81]
	v_mfma_f32_16x16x32_bf16 v[74:77], v[158:161], v[224:227], v[74:77]
	v_mfma_f32_16x16x32_bf16 v[118:121], v[162:165], v[178:181], v[118:121]
	v_mfma_f32_16x16x32_bf16 v[114:117], v[170:173], v[178:181], v[114:117]
	v_mfma_f32_16x16x32_bf16 v[102:105], v[162:165], v[186:189], v[102:105]
	v_mfma_f32_16x16x32_bf16 v[98:101], v[170:173], v[186:189], v[98:101]
	v_mfma_f32_16x16x32_bf16 v[86:89], v[162:165], v[202:205], v[86:89]
	v_mfma_f32_16x16x32_bf16 v[82:85], v[170:173], v[202:205], v[82:85]
	v_mfma_f32_16x16x32_bf16 v[70:73], v[162:165], v[220:223], v[70:73]
	v_mfma_f32_16x16x32_bf16 v[66:69], v[170:173], v[220:223], v[66:69]
	v_mfma_f32_16x16x32_bf16 v[118:121], v[166:169], v[182:185], v[118:121]
	v_mfma_f32_16x16x32_bf16 v[114:117], v[174:177], v[182:185], v[114:117]
	v_mfma_f32_16x16x32_bf16 v[102:105], v[166:169], v[190:193], v[102:105]
	v_mfma_f32_16x16x32_bf16 v[98:101], v[174:177], v[190:193], v[98:101]
	v_mfma_f32_16x16x32_bf16 v[86:89], v[166:169], v[206:209], v[86:89]
	v_mfma_f32_16x16x32_bf16 v[82:85], v[174:177], v[206:209], v[82:85]
	v_mfma_f32_16x16x32_bf16 v[70:73], v[166:169], v[224:227], v[70:73]
	v_mfma_f32_16x16x32_bf16 v[66:69], v[174:177], v[224:227], v[66:69]
	s_setprio 0
	s_barrier
	s_add_i32 s36, s45, s79
	v_lshl_add_u64 v[194:195], v[194:195], 0, s[84:85]
	s_mov_b32 m0, s36
	ds_read_b128 v[178:181], v149 offset:49152
	ds_read_b128 v[182:185], v149 offset:50176
	ds_read_b128 v[186:189], v149 offset:51200
	ds_read_b128 v[190:193], v149 offset:52224
	ds_read_b128 v[202:205], v149 offset:53248
	ds_read_b128 v[206:209], v149 offset:54272
	ds_read_b128 v[220:223], v149 offset:55296
	ds_read_b128 v[224:227], v149 offset:56320
	global_load_lds_dwordx4 v[194:195], off
	v_lshl_add_u64 v[194:195], v[198:199], 0, s[84:85]
	s_add_i32 m0, s36, 0x2000
	s_add_i32 s36, s62, s79
	global_load_lds_dwordx4 v[194:195], off
	v_lshl_add_u64 v[194:195], v[200:201], 0, s[84:85]
	s_mov_b32 m0, s36
	s_nop 0
	global_load_lds_dwordx4 v[194:195], off
	v_lshl_add_u64 v[194:195], v[210:211], 0, s[84:85]
	s_add_i32 m0, s36, 0x2000
	s_nop 0
	global_load_lds_dwordx4 v[194:195], off
	v_lshl_add_u64 v[194:195], v[212:213], 0, s[84:85]
	s_mov_b32 m0, s46
	s_nop 0
	global_load_lds_dwordx4 v[194:195], off
	v_lshl_add_u64 v[194:195], v[214:215], 0, s[84:85]
	s_mov_b32 m0, s47
	s_nop 0
	global_load_lds_dwordx4 v[194:195], off
	s_waitcnt vmcnt(8)
	s_waitcnt lgkmcnt(0)
	s_barrier
	s_setprio 1
	s_waitcnt lgkmcnt(0)
	v_mfma_f32_16x16x32_bf16 v[62:65], v[144:147], v[178:181], v[62:65]
	v_mfma_f32_16x16x32_bf16 v[58:61], v[154:157], v[178:181], v[58:61]
	v_mfma_f32_16x16x32_bf16 v[46:49], v[144:147], v[186:189], v[46:49]
	v_mfma_f32_16x16x32_bf16 v[42:45], v[154:157], v[186:189], v[42:45]
	v_mfma_f32_16x16x32_bf16 v[30:33], v[144:147], v[202:205], v[30:33]
	v_mfma_f32_16x16x32_bf16 v[26:29], v[154:157], v[202:205], v[26:29]
	v_mfma_f32_16x16x32_bf16 v[14:17], v[144:147], v[220:223], v[14:17]
	v_mfma_f32_16x16x32_bf16 v[10:13], v[154:157], v[220:223], v[10:13]
	v_mfma_f32_16x16x32_bf16 v[62:65], v[150:153], v[182:185], v[62:65]
	v_mfma_f32_16x16x32_bf16 v[58:61], v[158:161], v[182:185], v[58:61]
	v_mfma_f32_16x16x32_bf16 v[46:49], v[150:153], v[190:193], v[46:49]
	v_mfma_f32_16x16x32_bf16 v[42:45], v[158:161], v[190:193], v[42:45]
	v_mfma_f32_16x16x32_bf16 v[30:33], v[150:153], v[206:209], v[30:33]
	v_mfma_f32_16x16x32_bf16 v[26:29], v[158:161], v[206:209], v[26:29]
	v_mfma_f32_16x16x32_bf16 v[14:17], v[150:153], v[224:227], v[14:17]
	v_mfma_f32_16x16x32_bf16 v[10:13], v[158:161], v[224:227], v[10:13]
	v_mfma_f32_16x16x32_bf16 v[54:57], v[162:165], v[178:181], v[54:57]
	v_mfma_f32_16x16x32_bf16 v[50:53], v[170:173], v[178:181], v[50:53]
	v_mfma_f32_16x16x32_bf16 v[38:41], v[162:165], v[186:189], v[38:41]
	v_mfma_f32_16x16x32_bf16 v[34:37], v[170:173], v[186:189], v[34:37]
	v_mfma_f32_16x16x32_bf16 v[22:25], v[162:165], v[202:205], v[22:25]
	v_mfma_f32_16x16x32_bf16 v[18:21], v[170:173], v[202:205], v[18:21]
	v_mfma_f32_16x16x32_bf16 v[6:9], v[162:165], v[220:223], v[6:9]
	v_mfma_f32_16x16x32_bf16 v[2:5], v[170:173], v[220:223], v[2:5]
	v_mfma_f32_16x16x32_bf16 v[54:57], v[166:169], v[182:185], v[54:57]
	v_mfma_f32_16x16x32_bf16 v[50:53], v[174:177], v[182:185], v[50:53]
	v_mfma_f32_16x16x32_bf16 v[38:41], v[166:169], v[190:193], v[38:41]
	v_mfma_f32_16x16x32_bf16 v[34:37], v[174:177], v[190:193], v[34:37]
	v_mfma_f32_16x16x32_bf16 v[22:25], v[166:169], v[206:209], v[22:25]
	v_mfma_f32_16x16x32_bf16 v[18:21], v[174:177], v[206:209], v[18:21]
	v_mfma_f32_16x16x32_bf16 v[6:9], v[166:169], v[224:227], v[6:9]
	v_mfma_f32_16x16x32_bf16 v[2:5], v[174:177], v[224:227], v[2:5]
	s_setprio 0
	s_barrier
	s_add_u32 s8, s8, 0x100
	s_addc_u32 s9, s9, 0
	s_add_u32 s59, s59, 0x100
	s_addc_u32 s60, s60, 0
	s_cmp_ge_u32 s61, s90
	s_mov_b32 s36, s61
	s_cbranch_scc0 .LBB0_352

.LBB0_438:
	s_add_i32 s58, s36, 2
	s_add_u32 s59, s34, 0x80
	s_addc_u32 s37, s35, 0
	s_add_i32 s62, 0, 0x10000
	s_cmp_eq_u32 s50, s36
	s_cselect_b32 s37, s9, s37
	s_cselect_b32 s36, s8, s59
	v_add_u32_e32 v144, s62, v147
	s_cselect_b32 s61, s21, s57
	s_cselect_b32 s60, s20, s56
	s_add_i32 s59, 0, 0x14000
	ds_read_b128 v[136:139], v144
	ds_read_b128 v[140:143], v144 offset:1024
	ds_read_b128 v[150:153], v144 offset:2048
	ds_read_b128 v[154:157], v144 offset:3072
	v_add_u32_e32 v144, s59, v147
	ds_read_b128 v[158:161], v144
	ds_read_b128 v[162:165], v144 offset:1024
	ds_read_b128 v[166:169], v144 offset:2048
	ds_read_b128 v[170:173], v144 offset:3072
	v_lshl_add_u64 v[144:145], s[34:35], 0, v[132:133]
	s_add_i32 m0, s79, 0xc000
	ds_read_b128 v[174:177], v149
	ds_read_b128 v[178:181], v149 offset:1024
	ds_read_b128 v[182:185], v149 offset:2048
	ds_read_b128 v[186:189], v149 offset:3072
	ds_read_b128 v[190:193], v149 offset:4096
	ds_read_b128 v[202:205], v149 offset:5120
	ds_read_b128 v[206:209], v149 offset:6144
	ds_read_b128 v[220:223], v149 offset:7168
	global_load_lds_dwordx4 v[144:145], off
	v_lshl_add_u64 v[144:145], s[34:35], 0, v[134:135]
	s_add_i32 m0, s79, 0xe000
	s_nop 0
	global_load_lds_dwordx4 v[144:145], off
	s_waitcnt vmcnt(8)
	s_waitcnt lgkmcnt(0)
	s_barrier
	s_setprio 1
	s_waitcnt lgkmcnt(0)
	v_mfma_f32_16x16x32_bf16 v[126:129], v[136:139], v[174:177], v[126:129]
	v_mfma_f32_16x16x32_bf16 v[98:101], v[150:153], v[174:177], v[98:101]
	v_mfma_f32_16x16x32_bf16 v[122:125], v[136:139], v[182:185], v[122:125]
	v_mfma_f32_16x16x32_bf16 v[94:97], v[150:153], v[182:185], v[94:97]
	v_mfma_f32_16x16x32_bf16 v[118:121], v[136:139], v[190:193], v[118:121]
	v_mfma_f32_16x16x32_bf16 v[86:89], v[150:153], v[190:193], v[86:89]
	v_mfma_f32_16x16x32_bf16 v[114:117], v[136:139], v[206:209], v[114:117]
	v_mfma_f32_16x16x32_bf16 v[82:85], v[150:153], v[206:209], v[82:85]
	v_mfma_f32_16x16x32_bf16 v[126:129], v[140:143], v[178:181], v[126:129]
	v_mfma_f32_16x16x32_bf16 v[98:101], v[154:157], v[178:181], v[98:101]
	v_mfma_f32_16x16x32_bf16 v[122:125], v[140:143], v[186:189], v[122:125]
	v_mfma_f32_16x16x32_bf16 v[94:97], v[154:157], v[186:189], v[94:97]
	v_mfma_f32_16x16x32_bf16 v[118:121], v[140:143], v[202:205], v[118:121]
	v_mfma_f32_16x16x32_bf16 v[86:89], v[154:157], v[202:205], v[86:89]
	v_mfma_f32_16x16x32_bf16 v[114:117], v[140:143], v[220:223], v[114:117]
	v_mfma_f32_16x16x32_bf16 v[82:85], v[154:157], v[220:223], v[82:85]
	v_mfma_f32_16x16x32_bf16 v[70:73], v[158:161], v[174:177], v[70:73]
	v_mfma_f32_16x16x32_bf16 v[42:45], v[166:169], v[174:177], v[42:45]
	v_mfma_f32_16x16x32_bf16 v[62:65], v[158:161], v[182:185], v[62:65]
	v_mfma_f32_16x16x32_bf16 v[34:37], v[166:169], v[182:185], v[34:37]
	v_mfma_f32_16x16x32_bf16 v[54:57], v[158:161], v[190:193], v[54:57]
	v_mfma_f32_16x16x32_bf16 v[26:29], v[166:169], v[190:193], v[26:29]
	v_mfma_f32_16x16x32_bf16 v[50:53], v[158:161], v[206:209], v[50:53]
	v_mfma_f32_16x16x32_bf16 v[18:21], v[166:169], v[206:209], v[18:21]
	v_mfma_f32_16x16x32_bf16 v[70:73], v[162:165], v[178:181], v[70:73]
	v_mfma_f32_16x16x32_bf16 v[42:45], v[170:173], v[178:181], v[42:45]
	v_mfma_f32_16x16x32_bf16 v[62:65], v[162:165], v[186:189], v[62:65]
	v_mfma_f32_16x16x32_bf16 v[34:37], v[170:173], v[186:189], v[34:37]
	v_mfma_f32_16x16x32_bf16 v[54:57], v[162:165], v[202:205], v[54:57]
	v_mfma_f32_16x16x32_bf16 v[26:29], v[170:173], v[202:205], v[26:29]
	v_mfma_f32_16x16x32_bf16 v[50:53], v[162:165], v[220:223], v[50:53]
	v_mfma_f32_16x16x32_bf16 v[18:21], v[170:173], v[220:223], v[18:21]
	s_setprio 0
	s_barrier
	s_add_i32 s62, s62, s78
	v_lshl_add_u64 v[144:145], s[60:61], 0, v[0:1]
	s_mov_b32 m0, s62
	ds_read_b128 v[174:177], v149 offset:16384
	ds_read_b128 v[178:181], v149 offset:17408
	ds_read_b128 v[182:185], v149 offset:18432
	ds_read_b128 v[186:189], v149 offset:19456
	ds_read_b128 v[190:193], v149 offset:20480
	ds_read_b128 v[202:205], v149 offset:21504
	ds_read_b128 v[206:209], v149 offset:22528
	ds_read_b128 v[220:223], v149 offset:23552
	global_load_lds_dwordx4 v[144:145], off
	s_add_i32 m0, s62, 0x2000
	v_lshl_add_u64 v[194:195], s[60:61], 0, v[130:131]
	s_add_u32 s60, s60, s80
	s_addc_u32 s61, s61, 0
	s_add_i32 s59, s59, s78
	global_load_lds_dwordx4 v[194:195], off
	v_lshl_add_u64 v[198:199], s[60:61], 0, v[0:1]
	s_mov_b32 m0, s59
	v_lshl_add_u64 v[200:201], s[60:61], 0, v[130:131]
	global_load_lds_dwordx4 v[198:199], off
	s_add_i32 m0, s59, 0x2000
	v_lshl_add_u64 v[210:211], s[36:37], 0, v[0:1]
	global_load_lds_dwordx4 v[200:201], off
	s_mov_b32 m0, s79
	v_lshl_add_u64 v[212:213], s[36:37], 0, v[130:131]
	global_load_lds_dwordx4 v[210:211], off
	s_mov_b32 m0, s46
	s_nop 0
	global_load_lds_dwordx4 v[212:213], off
	s_waitcnt vmcnt(8)
	s_waitcnt lgkmcnt(0)
	s_barrier
	s_setprio 1
	s_waitcnt lgkmcnt(0)
	v_mfma_f32_16x16x32_bf16 v[110:113], v[136:139], v[174:177], v[110:113]
	v_mfma_f32_16x16x32_bf16 v[78:81], v[150:153], v[174:177], v[78:81]
	v_mfma_f32_16x16x32_bf16 v[106:109], v[136:139], v[182:185], v[106:109]
	v_mfma_f32_16x16x32_bf16 v[74:77], v[150:153], v[182:185], v[74:77]
	v_mfma_f32_16x16x32_bf16 v[102:105], v[136:139], v[190:193], v[102:105]
	v_mfma_f32_16x16x32_bf16 v[66:69], v[150:153], v[190:193], v[66:69]
	v_mfma_f32_16x16x32_bf16 v[90:93], v[136:139], v[206:209], v[90:93]
	v_mfma_f32_16x16x32_bf16 v[58:61], v[150:153], v[206:209], v[58:61]
	v_mfma_f32_16x16x32_bf16 v[110:113], v[140:143], v[178:181], v[110:113]
	v_mfma_f32_16x16x32_bf16 v[78:81], v[154:157], v[178:181], v[78:81]
	v_mfma_f32_16x16x32_bf16 v[106:109], v[140:143], v[186:189], v[106:109]
	v_mfma_f32_16x16x32_bf16 v[74:77], v[154:157], v[186:189], v[74:77]
	v_mfma_f32_16x16x32_bf16 v[102:105], v[140:143], v[202:205], v[102:105]
	v_mfma_f32_16x16x32_bf16 v[66:69], v[154:157], v[202:205], v[66:69]
	v_mfma_f32_16x16x32_bf16 v[90:93], v[140:143], v[220:223], v[90:93]
	v_mfma_f32_16x16x32_bf16 v[58:61], v[154:157], v[220:223], v[58:61]
	v_mfma_f32_16x16x32_bf16 v[46:49], v[158:161], v[174:177], v[46:49]
	v_mfma_f32_16x16x32_bf16 v[14:17], v[166:169], v[174:177], v[14:17]
	v_mfma_f32_16x16x32_bf16 v[38:41], v[158:161], v[182:185], v[38:41]
	v_mfma_f32_16x16x32_bf16 v[10:13], v[166:169], v[182:185], v[10:13]
	v_mfma_f32_16x16x32_bf16 v[30:33], v[158:161], v[190:193], v[30:33]
	v_mfma_f32_16x16x32_bf16 v[6:9], v[166:169], v[190:193], v[6:9]
	v_mfma_f32_16x16x32_bf16 v[22:25], v[158:161], v[206:209], v[22:25]
	v_mfma_f32_16x16x32_bf16 v[2:5], v[166:169], v[206:209], v[2:5]
	v_mfma_f32_16x16x32_bf16 v[46:49], v[162:165], v[178:181], v[46:49]
	v_mfma_f32_16x16x32_bf16 v[14:17], v[170:173], v[178:181], v[14:17]
	v_mfma_f32_16x16x32_bf16 v[38:41], v[162:165], v[186:189], v[38:41]
	v_mfma_f32_16x16x32_bf16 v[10:13], v[170:173], v[186:189], v[10:13]
	v_mfma_f32_16x16x32_bf16 v[30:33], v[162:165], v[202:205], v[30:33]
	v_mfma_f32_16x16x32_bf16 v[6:9], v[170:173], v[202:205], v[6:9]
	v_mfma_f32_16x16x32_bf16 v[22:25], v[162:165], v[220:223], v[22:25]
	v_mfma_f32_16x16x32_bf16 v[2:5], v[170:173], v[220:223], v[2:5]
	s_setprio 0
	s_barrier
	s_add_i32 s59, 0, 0x18000
	s_add_i32 s60, 0, 0x1c000
	v_add_u32_e32 v154, s59, v147
	v_add_u32_e32 v170, s60, v147
	ds_read_b128 v[136:139], v154
	ds_read_b128 v[140:143], v154 offset:1024
	ds_read_b128 v[150:153], v154 offset:2048
	ds_read_b128 v[154:157], v154 offset:3072
	ds_read_b128 v[158:161], v170
	ds_read_b128 v[162:165], v170 offset:1024
	ds_read_b128 v[166:169], v170 offset:2048
	ds_read_b128 v[170:173], v170 offset:3072
	s_add_u32 s36, s36, s80
	s_addc_u32 s37, s37, 0
	s_mov_b32 m0, s47
	v_lshl_add_u64 v[214:215], s[36:37], 0, v[0:1]
	ds_read_b128 v[174:177], v149 offset:32768
	ds_read_b128 v[178:181], v149 offset:33792
	ds_read_b128 v[182:185], v149 offset:34816
	ds_read_b128 v[186:189], v149 offset:35840
	ds_read_b128 v[190:193], v149 offset:36864
	ds_read_b128 v[202:205], v149 offset:37888
	ds_read_b128 v[206:209], v149 offset:38912
	ds_read_b128 v[220:223], v149 offset:39936
	global_load_lds_dwordx4 v[214:215], off
	v_lshl_add_u64 v[214:215], s[36:37], 0, v[130:131]
	s_mov_b32 m0, s82
	s_nop 0
	global_load_lds_dwordx4 v[214:215], off
	s_waitcnt vmcnt(8)
	s_waitcnt lgkmcnt(0)
	s_barrier
	s_setprio 1
	s_waitcnt lgkmcnt(0)
	v_mfma_f32_16x16x32_bf16 v[126:129], v[136:139], v[174:177], v[126:129]
	v_mfma_f32_16x16x32_bf16 v[98:101], v[150:153], v[174:177], v[98:101]
	v_mfma_f32_16x16x32_bf16 v[122:125], v[136:139], v[182:185], v[122:125]
	v_mfma_f32_16x16x32_bf16 v[94:97], v[150:153], v[182:185], v[94:97]
	v_mfma_f32_16x16x32_bf16 v[118:121], v[136:139], v[190:193], v[118:121]
	v_mfma_f32_16x16x32_bf16 v[86:89], v[150:153], v[190:193], v[86:89]
	v_mfma_f32_16x16x32_bf16 v[114:117], v[136:139], v[206:209], v[114:117]
	v_mfma_f32_16x16x32_bf16 v[82:85], v[150:153], v[206:209], v[82:85]
	v_mfma_f32_16x16x32_bf16 v[126:129], v[140:143], v[178:181], v[126:129]
	v_mfma_f32_16x16x32_bf16 v[98:101], v[154:157], v[178:181], v[98:101]
	v_mfma_f32_16x16x32_bf16 v[122:125], v[140:143], v[186:189], v[122:125]
	v_mfma_f32_16x16x32_bf16 v[94:97], v[154:157], v[186:189], v[94:97]
	v_mfma_f32_16x16x32_bf16 v[118:121], v[140:143], v[202:205], v[118:121]
	v_mfma_f32_16x16x32_bf16 v[86:89], v[154:157], v[202:205], v[86:89]
	v_mfma_f32_16x16x32_bf16 v[114:117], v[140:143], v[220:223], v[114:117]
	v_mfma_f32_16x16x32_bf16 v[82:85], v[154:157], v[220:223], v[82:85]
	v_mfma_f32_16x16x32_bf16 v[70:73], v[158:161], v[174:177], v[70:73]
	v_mfma_f32_16x16x32_bf16 v[42:45], v[166:169], v[174:177], v[42:45]
	v_mfma_f32_16x16x32_bf16 v[62:65], v[158:161], v[182:185], v[62:65]
	v_mfma_f32_16x16x32_bf16 v[34:37], v[166:169], v[182:185], v[34:37]
	v_mfma_f32_16x16x32_bf16 v[54:57], v[158:161], v[190:193], v[54:57]
	v_mfma_f32_16x16x32_bf16 v[26:29], v[166:169], v[190:193], v[26:29]
	v_mfma_f32_16x16x32_bf16 v[50:53], v[158:161], v[206:209], v[50:53]
	v_mfma_f32_16x16x32_bf16 v[18:21], v[166:169], v[206:209], v[18:21]
	v_mfma_f32_16x16x32_bf16 v[70:73], v[162:165], v[178:181], v[70:73]
	v_mfma_f32_16x16x32_bf16 v[42:45], v[170:173], v[178:181], v[42:45]
	v_mfma_f32_16x16x32_bf16 v[62:65], v[162:165], v[186:189], v[62:65]
	v_mfma_f32_16x16x32_bf16 v[34:37], v[170:173], v[186:189], v[34:37]
	v_mfma_f32_16x16x32_bf16 v[54:57], v[162:165], v[202:205], v[54:57]
	v_mfma_f32_16x16x32_bf16 v[26:29], v[170:173], v[202:205], v[26:29]
	v_mfma_f32_16x16x32_bf16 v[50:53], v[162:165], v[220:223], v[50:53]
	v_mfma_f32_16x16x32_bf16 v[18:21], v[170:173], v[220:223], v[18:21]
	s_setprio 0
	s_barrier
	s_add_i32 s36, s59, s78
	v_lshl_add_u64 v[144:145], v[144:145], 0, s[84:85]
	s_mov_b32 m0, s36
	ds_read_b128 v[174:177], v149 offset:49152
	ds_read_b128 v[178:181], v149 offset:50176
	ds_read_b128 v[182:185], v149 offset:51200
	ds_read_b128 v[186:189], v149 offset:52224
	ds_read_b128 v[190:193], v149 offset:53248
	ds_read_b128 v[202:205], v149 offset:54272
	ds_read_b128 v[206:209], v149 offset:55296
	ds_read_b128 v[220:223], v149 offset:56320
	global_load_lds_dwordx4 v[144:145], off
	v_lshl_add_u64 v[144:145], v[194:195], 0, s[84:85]
	s_add_i32 m0, s36, 0x2000
	s_add_i32 s36, s60, s78
	global_load_lds_dwordx4 v[144:145], off
	v_lshl_add_u64 v[144:145], v[198:199], 0, s[84:85]
	s_mov_b32 m0, s36
	s_nop 0
	global_load_lds_dwordx4 v[144:145], off
	v_lshl_add_u64 v[144:145], v[200:201], 0, s[84:85]
	s_add_i32 m0, s36, 0x2000
	s_nop 0
	global_load_lds_dwordx4 v[144:145], off
	v_lshl_add_u64 v[144:145], v[210:211], 0, s[84:85]
	s_mov_b32 m0, s48
	s_nop 0
	global_load_lds_dwordx4 v[144:145], off
	v_lshl_add_u64 v[144:145], v[212:213], 0, s[84:85]
	s_mov_b32 m0, s49
	s_nop 0
	global_load_lds_dwordx4 v[144:145], off
	s_waitcnt vmcnt(8)
	s_waitcnt lgkmcnt(0)
	s_barrier
	s_setprio 1
	s_waitcnt lgkmcnt(0)
	v_mfma_f32_16x16x32_bf16 v[110:113], v[136:139], v[174:177], v[110:113]
	v_mfma_f32_16x16x32_bf16 v[78:81], v[150:153], v[174:177], v[78:81]
	v_mfma_f32_16x16x32_bf16 v[106:109], v[136:139], v[182:185], v[106:109]
	v_mfma_f32_16x16x32_bf16 v[74:77], v[150:153], v[182:185], v[74:77]
	v_mfma_f32_16x16x32_bf16 v[102:105], v[136:139], v[190:193], v[102:105]
	v_mfma_f32_16x16x32_bf16 v[66:69], v[150:153], v[190:193], v[66:69]
	v_mfma_f32_16x16x32_bf16 v[90:93], v[136:139], v[206:209], v[90:93]
	v_mfma_f32_16x16x32_bf16 v[58:61], v[150:153], v[206:209], v[58:61]
	v_mfma_f32_16x16x32_bf16 v[110:113], v[140:143], v[178:181], v[110:113]
	v_mfma_f32_16x16x32_bf16 v[78:81], v[154:157], v[178:181], v[78:81]
	v_mfma_f32_16x16x32_bf16 v[106:109], v[140:143], v[186:189], v[106:109]
	v_mfma_f32_16x16x32_bf16 v[74:77], v[154:157], v[186:189], v[74:77]
	v_mfma_f32_16x16x32_bf16 v[102:105], v[140:143], v[202:205], v[102:105]
	v_mfma_f32_16x16x32_bf16 v[66:69], v[154:157], v[202:205], v[66:69]
	v_mfma_f32_16x16x32_bf16 v[90:93], v[140:143], v[220:223], v[90:93]
	v_mfma_f32_16x16x32_bf16 v[58:61], v[154:157], v[220:223], v[58:61]
	v_mfma_f32_16x16x32_bf16 v[46:49], v[158:161], v[174:177], v[46:49]
	v_mfma_f32_16x16x32_bf16 v[14:17], v[166:169], v[174:177], v[14:17]
	v_mfma_f32_16x16x32_bf16 v[38:41], v[158:161], v[182:185], v[38:41]
	v_mfma_f32_16x16x32_bf16 v[10:13], v[166:169], v[182:185], v[10:13]
	v_mfma_f32_16x16x32_bf16 v[30:33], v[158:161], v[190:193], v[30:33]
	v_mfma_f32_16x16x32_bf16 v[6:9], v[166:169], v[190:193], v[6:9]
	v_mfma_f32_16x16x32_bf16 v[22:25], v[158:161], v[206:209], v[22:25]
	v_mfma_f32_16x16x32_bf16 v[2:5], v[166:169], v[206:209], v[2:5]
	v_mfma_f32_16x16x32_bf16 v[46:49], v[162:165], v[178:181], v[46:49]
	v_mfma_f32_16x16x32_bf16 v[14:17], v[170:173], v[178:181], v[14:17]
	v_mfma_f32_16x16x32_bf16 v[38:41], v[162:165], v[186:189], v[38:41]
	v_mfma_f32_16x16x32_bf16 v[10:13], v[170:173], v[186:189], v[10:13]
	v_mfma_f32_16x16x32_bf16 v[30:33], v[162:165], v[202:205], v[30:33]
	v_mfma_f32_16x16x32_bf16 v[6:9], v[170:173], v[202:205], v[6:9]
	v_mfma_f32_16x16x32_bf16 v[22:25], v[162:165], v[220:223], v[22:25]
	v_mfma_f32_16x16x32_bf16 v[2:5], v[170:173], v[220:223], v[2:5]
	s_setprio 0
	s_barrier
	s_add_u32 s34, s34, 0x100
	s_addc_u32 s35, s35, 0
	s_add_u32 s56, s56, 0x100
	s_addc_u32 s57, s57, 0
	s_cmp_ge_u32 s58, s87
	s_mov_b32 s36, s58
	s_cbranch_scc0 .LBB0_438
	s_and_b64 vcc, exec, s[10:11]
	s_cbranch_vccz .LBB0_441
	s_barrier

.LBB0_483:
	s_add_i32 s61, s38, 2
	s_add_u32 s62, s20, s36
	s_addc_u32 s39, s21, s37
	s_add_u32 s64, s4, s36
	s_addc_u32 s63, s5, s37
	s_add_i32 s65, 0, 0x10000
	s_cmp_eq_u32 s56, s38
	s_cselect_b32 s39, s11, s39
	s_cselect_b32 s38, s10, s62
	v_add_u32_e32 v147, s65, v145
	s_cselect_b32 s63, s35, s63
	s_cselect_b32 s62, s34, s64
	s_add_i32 s64, 0, 0x14000
	ds_read_b128 v[148:151], v147
	ds_read_b128 v[152:155], v147 offset:1024
	ds_read_b128 v[156:159], v147 offset:2048
	ds_read_b128 v[160:163], v147 offset:3072
	v_add_u32_e32 v147, s64, v145
	ds_read_b128 v[164:167], v147
	ds_read_b128 v[168:171], v147 offset:1024
	ds_read_b128 v[172:175], v147 offset:2048
	ds_read_b128 v[176:179], v147 offset:3072
	v_lshl_add_u64 v[194:195], s[20:21], 0, v[142:143]
	s_add_i32 m0, s48, 0xc000
	ds_read_b128 v[180:183], v146
	ds_read_b128 v[184:187], v146 offset:1024
	ds_read_b128 v[190:193], v146 offset:2048
	ds_read_b128 v[202:205], v146 offset:3072
	ds_read_b128 v[206:209], v146 offset:4096
	ds_read_b128 v[220:223], v146 offset:5120
	ds_read_b128 v[224:227], v146 offset:6144
	ds_read_b128 v[228:231], v146 offset:7168
	global_load_lds_dwordx4 v[194:195], off
	v_lshl_add_u64 v[194:195], s[20:21], 0, v[140:141]
	s_add_i32 m0, s48, 0xe000
	s_nop 0
	global_load_lds_dwordx4 v[194:195], off
	s_waitcnt vmcnt(8)
	s_waitcnt lgkmcnt(0)
	s_barrier
	s_setprio 1
	s_waitcnt lgkmcnt(0)
	v_mfma_f32_16x16x32_bf16 v[126:129], v[148:151], v[180:183], v[126:129]
	v_mfma_f32_16x16x32_bf16 v[122:125], v[156:159], v[180:183], v[122:125]
	v_mfma_f32_16x16x32_bf16 v[118:121], v[148:151], v[190:193], v[118:121]
	v_mfma_f32_16x16x32_bf16 v[114:117], v[156:159], v[190:193], v[114:117]
	v_mfma_f32_16x16x32_bf16 v[110:113], v[148:151], v[206:209], v[110:113]
	v_mfma_f32_16x16x32_bf16 v[106:109], v[156:159], v[206:209], v[106:109]
	v_mfma_f32_16x16x32_bf16 v[102:105], v[148:151], v[224:227], v[102:105]
	v_mfma_f32_16x16x32_bf16 v[98:101], v[156:159], v[224:227], v[98:101]
	v_mfma_f32_16x16x32_bf16 v[126:129], v[152:155], v[184:187], v[126:129]
	v_mfma_f32_16x16x32_bf16 v[122:125], v[160:163], v[184:187], v[122:125]
	v_mfma_f32_16x16x32_bf16 v[118:121], v[152:155], v[202:205], v[118:121]
	v_mfma_f32_16x16x32_bf16 v[114:117], v[160:163], v[202:205], v[114:117]
	v_mfma_f32_16x16x32_bf16 v[110:113], v[152:155], v[220:223], v[110:113]
	v_mfma_f32_16x16x32_bf16 v[106:109], v[160:163], v[220:223], v[106:109]
	v_mfma_f32_16x16x32_bf16 v[102:105], v[152:155], v[228:231], v[102:105]
	v_mfma_f32_16x16x32_bf16 v[98:101], v[160:163], v[228:231], v[98:101]
	v_mfma_f32_16x16x32_bf16 v[62:65], v[164:167], v[180:183], v[62:65]
	v_mfma_f32_16x16x32_bf16 v[58:61], v[172:175], v[180:183], v[58:61]
	v_mfma_f32_16x16x32_bf16 v[54:57], v[164:167], v[190:193], v[54:57]
	v_mfma_f32_16x16x32_bf16 v[50:53], v[172:175], v[190:193], v[50:53]
	v_mfma_f32_16x16x32_bf16 v[46:49], v[164:167], v[206:209], v[46:49]
	v_mfma_f32_16x16x32_bf16 v[42:45], v[172:175], v[206:209], v[42:45]
	v_mfma_f32_16x16x32_bf16 v[38:41], v[164:167], v[224:227], v[38:41]
	v_mfma_f32_16x16x32_bf16 v[34:37], v[172:175], v[224:227], v[34:37]
	v_mfma_f32_16x16x32_bf16 v[62:65], v[168:171], v[184:187], v[62:65]
	v_mfma_f32_16x16x32_bf16 v[58:61], v[176:179], v[184:187], v[58:61]
	v_mfma_f32_16x16x32_bf16 v[54:57], v[168:171], v[202:205], v[54:57]
	v_mfma_f32_16x16x32_bf16 v[50:53], v[176:179], v[202:205], v[50:53]
	v_mfma_f32_16x16x32_bf16 v[46:49], v[168:171], v[220:223], v[46:49]
	v_mfma_f32_16x16x32_bf16 v[42:45], v[176:179], v[220:223], v[42:45]
	v_mfma_f32_16x16x32_bf16 v[38:41], v[168:171], v[228:231], v[38:41]
	v_mfma_f32_16x16x32_bf16 v[34:37], v[176:179], v[228:231], v[34:37]
	s_setprio 0
	s_barrier
	s_add_i32 s65, s65, s47
	v_lshl_add_u64 v[194:195], s[62:63], 0, v[0:1]
	s_mov_b32 m0, s65
	ds_read_b128 v[180:183], v146 offset:16384
	ds_read_b128 v[184:187], v146 offset:17408
	ds_read_b128 v[190:193], v146 offset:18432
	ds_read_b128 v[202:205], v146 offset:19456
	ds_read_b128 v[206:209], v146 offset:20480
	ds_read_b128 v[220:223], v146 offset:21504
	ds_read_b128 v[224:227], v146 offset:22528
	ds_read_b128 v[228:231], v146 offset:23552
	global_load_lds_dwordx4 v[194:195], off
	s_add_i32 m0, s65, 0x2000
	v_lshl_add_u64 v[198:199], s[62:63], 0, v[134:135]
	s_add_u32 s62, s62, s80
	s_addc_u32 s63, s63, 0
	s_add_i32 s64, s64, s47
	global_load_lds_dwordx4 v[198:199], off
	v_lshl_add_u64 v[200:201], s[62:63], 0, v[0:1]
	s_mov_b32 m0, s64
	v_lshl_add_u64 v[210:211], s[62:63], 0, v[134:135]
	global_load_lds_dwordx4 v[200:201], off
	s_add_i32 m0, s64, 0x2000
	v_lshl_add_u64 v[212:213], s[38:39], 0, v[130:131]
	global_load_lds_dwordx4 v[210:211], off
	s_mov_b32 m0, s48
	v_lshl_add_u64 v[214:215], s[38:39], 0, v[132:133]
	global_load_lds_dwordx4 v[212:213], off
	s_mov_b32 m0, s50
	s_nop 0
	global_load_lds_dwordx4 v[214:215], off
	s_waitcnt vmcnt(8)
	s_waitcnt lgkmcnt(0)
	s_barrier
	s_setprio 1
	s_waitcnt lgkmcnt(0)
	v_mfma_f32_16x16x32_bf16 v[94:97], v[148:151], v[180:183], v[94:97]
	v_mfma_f32_16x16x32_bf16 v[90:93], v[156:159], v[180:183], v[90:93]
	v_mfma_f32_16x16x32_bf16 v[86:89], v[148:151], v[190:193], v[86:89]
	v_mfma_f32_16x16x32_bf16 v[82:85], v[156:159], v[190:193], v[82:85]
	v_mfma_f32_16x16x32_bf16 v[78:81], v[148:151], v[206:209], v[78:81]
	v_mfma_f32_16x16x32_bf16 v[74:77], v[156:159], v[206:209], v[74:77]
	v_mfma_f32_16x16x32_bf16 v[70:73], v[148:151], v[224:227], v[70:73]
	v_mfma_f32_16x16x32_bf16 v[66:69], v[156:159], v[224:227], v[66:69]
	v_mfma_f32_16x16x32_bf16 v[94:97], v[152:155], v[184:187], v[94:97]
	v_mfma_f32_16x16x32_bf16 v[90:93], v[160:163], v[184:187], v[90:93]
	v_mfma_f32_16x16x32_bf16 v[86:89], v[152:155], v[202:205], v[86:89]
	v_mfma_f32_16x16x32_bf16 v[82:85], v[160:163], v[202:205], v[82:85]
	v_mfma_f32_16x16x32_bf16 v[78:81], v[152:155], v[220:223], v[78:81]
	v_mfma_f32_16x16x32_bf16 v[74:77], v[160:163], v[220:223], v[74:77]
	v_mfma_f32_16x16x32_bf16 v[70:73], v[152:155], v[228:231], v[70:73]
	v_mfma_f32_16x16x32_bf16 v[66:69], v[160:163], v[228:231], v[66:69]
	v_mfma_f32_16x16x32_bf16 v[30:33], v[164:167], v[180:183], v[30:33]
	v_mfma_f32_16x16x32_bf16 v[26:29], v[172:175], v[180:183], v[26:29]
	v_mfma_f32_16x16x32_bf16 v[22:25], v[164:167], v[190:193], v[22:25]
	v_mfma_f32_16x16x32_bf16 v[18:21], v[172:175], v[190:193], v[18:21]
	v_mfma_f32_16x16x32_bf16 v[14:17], v[164:167], v[206:209], v[14:17]
	v_mfma_f32_16x16x32_bf16 v[10:13], v[172:175], v[206:209], v[10:13]
	v_mfma_f32_16x16x32_bf16 v[6:9], v[164:167], v[224:227], v[6:9]
	v_mfma_f32_16x16x32_bf16 v[2:5], v[172:175], v[224:227], v[2:5]
	v_mfma_f32_16x16x32_bf16 v[30:33], v[168:171], v[184:187], v[30:33]
	v_mfma_f32_16x16x32_bf16 v[26:29], v[176:179], v[184:187], v[26:29]
	v_mfma_f32_16x16x32_bf16 v[22:25], v[168:171], v[202:205], v[22:25]
	v_mfma_f32_16x16x32_bf16 v[18:21], v[176:179], v[202:205], v[18:21]
	v_mfma_f32_16x16x32_bf16 v[14:17], v[168:171], v[220:223], v[14:17]
	v_mfma_f32_16x16x32_bf16 v[10:13], v[176:179], v[220:223], v[10:13]
	v_mfma_f32_16x16x32_bf16 v[6:9], v[168:171], v[228:231], v[6:9]
	v_mfma_f32_16x16x32_bf16 v[2:5], v[176:179], v[228:231], v[2:5]
	s_setprio 0
	s_barrier
	s_add_i32 s62, 0, 0x18000
	v_add_u32_e32 v147, s62, v145
	s_add_i32 s63, 0, 0x1c000
	ds_read_b128 v[148:151], v147
	ds_read_b128 v[152:155], v147 offset:1024
	ds_read_b128 v[156:159], v147 offset:2048
	ds_read_b128 v[160:163], v147 offset:3072
	v_add_u32_e32 v147, s63, v145
	ds_read_b128 v[164:167], v147
	ds_read_b128 v[168:171], v147 offset:1024
	ds_read_b128 v[172:175], v147 offset:2048
	ds_read_b128 v[176:179], v147 offset:3072
	s_add_u32 s38, s38, s80
	s_addc_u32 s39, s39, 0
	s_mov_b32 m0, s51
	v_lshl_add_u64 v[216:217], s[38:39], 0, v[130:131]
	ds_read_b128 v[180:183], v146 offset:32768
	ds_read_b128 v[184:187], v146 offset:33792
	ds_read_b128 v[190:193], v146 offset:34816
	ds_read_b128 v[202:205], v146 offset:35840
	ds_read_b128 v[206:209], v146 offset:36864
	ds_read_b128 v[220:223], v146 offset:37888
	ds_read_b128 v[224:227], v146 offset:38912
	ds_read_b128 v[228:231], v146 offset:39936
	global_load_lds_dwordx4 v[216:217], off
	v_lshl_add_u64 v[216:217], s[38:39], 0, v[132:133]
	s_mov_b32 m0, s52
	s_nop 0
	global_load_lds_dwordx4 v[216:217], off
	s_waitcnt vmcnt(8)
	s_waitcnt lgkmcnt(0)
	s_barrier
	s_setprio 1
	s_waitcnt lgkmcnt(0)
	v_mfma_f32_16x16x32_bf16 v[126:129], v[148:151], v[180:183], v[126:129]
	v_mfma_f32_16x16x32_bf16 v[122:125], v[156:159], v[180:183], v[122:125]
	v_mfma_f32_16x16x32_bf16 v[118:121], v[148:151], v[190:193], v[118:121]
	v_mfma_f32_16x16x32_bf16 v[114:117], v[156:159], v[190:193], v[114:117]
	v_mfma_f32_16x16x32_bf16 v[110:113], v[148:151], v[206:209], v[110:113]
	v_mfma_f32_16x16x32_bf16 v[106:109], v[156:159], v[206:209], v[106:109]
	v_mfma_f32_16x16x32_bf16 v[102:105], v[148:151], v[224:227], v[102:105]
	v_mfma_f32_16x16x32_bf16 v[98:101], v[156:159], v[224:227], v[98:101]
	v_mfma_f32_16x16x32_bf16 v[126:129], v[152:155], v[184:187], v[126:129]
	v_mfma_f32_16x16x32_bf16 v[122:125], v[160:163], v[184:187], v[122:125]
	v_mfma_f32_16x16x32_bf16 v[118:121], v[152:155], v[202:205], v[118:121]
	v_mfma_f32_16x16x32_bf16 v[114:117], v[160:163], v[202:205], v[114:117]
	v_mfma_f32_16x16x32_bf16 v[110:113], v[152:155], v[220:223], v[110:113]
	v_mfma_f32_16x16x32_bf16 v[106:109], v[160:163], v[220:223], v[106:109]
	v_mfma_f32_16x16x32_bf16 v[102:105], v[152:155], v[228:231], v[102:105]
	v_mfma_f32_16x16x32_bf16 v[98:101], v[160:163], v[228:231], v[98:101]
	v_mfma_f32_16x16x32_bf16 v[62:65], v[164:167], v[180:183], v[62:65]
	v_mfma_f32_16x16x32_bf16 v[58:61], v[172:175], v[180:183], v[58:61]
	v_mfma_f32_16x16x32_bf16 v[54:57], v[164:167], v[190:193], v[54:57]
	v_mfma_f32_16x16x32_bf16 v[50:53], v[172:175], v[190:193], v[50:53]
	v_mfma_f32_16x16x32_bf16 v[46:49], v[164:167], v[206:209], v[46:49]
	v_mfma_f32_16x16x32_bf16 v[42:45], v[172:175], v[206:209], v[42:45]
	v_mfma_f32_16x16x32_bf16 v[38:41], v[164:167], v[224:227], v[38:41]
	v_mfma_f32_16x16x32_bf16 v[34:37], v[172:175], v[224:227], v[34:37]
	v_mfma_f32_16x16x32_bf16 v[62:65], v[168:171], v[184:187], v[62:65]
	v_mfma_f32_16x16x32_bf16 v[58:61], v[176:179], v[184:187], v[58:61]
	v_mfma_f32_16x16x32_bf16 v[54:57], v[168:171], v[202:205], v[54:57]
	v_mfma_f32_16x16x32_bf16 v[50:53], v[176:179], v[202:205], v[50:53]
	v_mfma_f32_16x16x32_bf16 v[46:49], v[168:171], v[220:223], v[46:49]
	v_mfma_f32_16x16x32_bf16 v[42:45], v[176:179], v[220:223], v[42:45]
	v_mfma_f32_16x16x32_bf16 v[38:41], v[168:171], v[228:231], v[38:41]
	v_mfma_f32_16x16x32_bf16 v[34:37], v[176:179], v[228:231], v[34:37]
	s_setprio 0
	s_barrier
	s_add_i32 s38, s62, s47
	v_lshl_add_u64 v[194:195], v[194:195], 0, s[84:85]
	s_mov_b32 m0, s38
	ds_read_b128 v[180:183], v146 offset:49152
	ds_read_b128 v[184:187], v146 offset:50176
	ds_read_b128 v[190:193], v146 offset:51200
	ds_read_b128 v[202:205], v146 offset:52224
	ds_read_b128 v[206:209], v146 offset:53248
	ds_read_b128 v[220:223], v146 offset:54272
	ds_read_b128 v[224:227], v146 offset:55296
	ds_read_b128 v[228:231], v146 offset:56320
	global_load_lds_dwordx4 v[194:195], off
	v_lshl_add_u64 v[194:195], v[198:199], 0, s[84:85]
	s_add_i32 m0, s38, 0x2000
	s_add_i32 s38, s63, s47
	global_load_lds_dwordx4 v[194:195], off
	v_lshl_add_u64 v[194:195], v[200:201], 0, s[84:85]
	s_mov_b32 m0, s38
	s_nop 0
	global_load_lds_dwordx4 v[194:195], off
	v_lshl_add_u64 v[194:195], v[210:211], 0, s[84:85]
	s_add_i32 m0, s38, 0x2000
	s_nop 0
	global_load_lds_dwordx4 v[194:195], off
	v_lshl_add_u64 v[194:195], v[212:213], 0, s[84:85]
	s_mov_b32 m0, s54
	s_nop 0
	global_load_lds_dwordx4 v[194:195], off
	v_lshl_add_u64 v[194:195], v[214:215], 0, s[84:85]
	s_mov_b32 m0, s55
	s_nop 0
	global_load_lds_dwordx4 v[194:195], off
	s_waitcnt vmcnt(8)
	s_waitcnt lgkmcnt(0)
	s_barrier
	s_setprio 1
	s_waitcnt lgkmcnt(0)
	v_mfma_f32_16x16x32_bf16 v[94:97], v[148:151], v[180:183], v[94:97]
	v_mfma_f32_16x16x32_bf16 v[90:93], v[156:159], v[180:183], v[90:93]
	v_mfma_f32_16x16x32_bf16 v[86:89], v[148:151], v[190:193], v[86:89]
	v_mfma_f32_16x16x32_bf16 v[82:85], v[156:159], v[190:193], v[82:85]
	v_mfma_f32_16x16x32_bf16 v[78:81], v[148:151], v[206:209], v[78:81]
	v_mfma_f32_16x16x32_bf16 v[74:77], v[156:159], v[206:209], v[74:77]
	v_mfma_f32_16x16x32_bf16 v[70:73], v[148:151], v[224:227], v[70:73]
	v_mfma_f32_16x16x32_bf16 v[66:69], v[156:159], v[224:227], v[66:69]
	v_mfma_f32_16x16x32_bf16 v[94:97], v[152:155], v[184:187], v[94:97]
	v_mfma_f32_16x16x32_bf16 v[90:93], v[160:163], v[184:187], v[90:93]
	v_mfma_f32_16x16x32_bf16 v[86:89], v[152:155], v[202:205], v[86:89]
	v_mfma_f32_16x16x32_bf16 v[82:85], v[160:163], v[202:205], v[82:85]
	v_mfma_f32_16x16x32_bf16 v[78:81], v[152:155], v[220:223], v[78:81]
	v_mfma_f32_16x16x32_bf16 v[74:77], v[160:163], v[220:223], v[74:77]
	v_mfma_f32_16x16x32_bf16 v[70:73], v[152:155], v[228:231], v[70:73]
	v_mfma_f32_16x16x32_bf16 v[66:69], v[160:163], v[228:231], v[66:69]
	v_mfma_f32_16x16x32_bf16 v[30:33], v[164:167], v[180:183], v[30:33]
	v_mfma_f32_16x16x32_bf16 v[26:29], v[172:175], v[180:183], v[26:29]
	v_mfma_f32_16x16x32_bf16 v[22:25], v[164:167], v[190:193], v[22:25]
	v_mfma_f32_16x16x32_bf16 v[18:21], v[172:175], v[190:193], v[18:21]
	v_mfma_f32_16x16x32_bf16 v[14:17], v[164:167], v[206:209], v[14:17]
	v_mfma_f32_16x16x32_bf16 v[10:13], v[172:175], v[206:209], v[10:13]
	v_mfma_f32_16x16x32_bf16 v[6:9], v[164:167], v[224:227], v[6:9]
	v_mfma_f32_16x16x32_bf16 v[2:5], v[172:175], v[224:227], v[2:5]
	v_mfma_f32_16x16x32_bf16 v[30:33], v[168:171], v[184:187], v[30:33]
	v_mfma_f32_16x16x32_bf16 v[26:29], v[176:179], v[184:187], v[26:29]
	v_mfma_f32_16x16x32_bf16 v[22:25], v[168:171], v[202:205], v[22:25]
	v_mfma_f32_16x16x32_bf16 v[18:21], v[176:179], v[202:205], v[18:21]
	v_mfma_f32_16x16x32_bf16 v[14:17], v[168:171], v[220:223], v[14:17]
	v_mfma_f32_16x16x32_bf16 v[10:13], v[176:179], v[220:223], v[10:13]
	v_mfma_f32_16x16x32_bf16 v[6:9], v[168:171], v[228:231], v[6:9]
	v_mfma_f32_16x16x32_bf16 v[2:5], v[176:179], v[228:231], v[2:5]
	s_setprio 0
	s_barrier
	s_add_u32 s36, s36, 0x100
	s_addc_u32 s37, s37, 0
	v_lshl_add_u64 v[142:143], v[142:143], 0, s[88:89]
	v_lshl_add_u64 v[140:141], v[140:141], 0, s[88:89]
	s_cmp_ge_u32 s61, s53
	s_mov_b32 s38, s61
	s_cbranch_scc0 .LBB0_483
	s_and_b64 vcc, exec, s[8:9]
	s_cbranch_vccnz .LBB0_471
	v_mov_b32_e32 v2, 0
	s_mov_b32 s2, s58
	s_mov_b32 s78, s59
	s_mov_b64 s[4:5], s[34:35]
	s_mov_b64 s[20:21], s[10:11]
	s_mov_b32 s57, s60
	v_mov_b32_e32 v3, v2
	v_mov_b32_e32 v4, v2
	v_mov_b32_e32 v5, v2
	v_mov_b32_e32 v6, v2
	v_mov_b32_e32 v7, v2
	v_mov_b32_e32 v8, v2
	v_mov_b32_e32 v9, v2
	v_mov_b32_e32 v10, v2
	v_mov_b32_e32 v11, v2
	v_mov_b32_e32 v12, v2
	v_mov_b32_e32 v13, v2
	v_mov_b32_e32 v14, v2
	v_mov_b32_e32 v15, v2
	v_mov_b32_e32 v16, v2
	v_mov_b32_e32 v17, v2
	v_mov_b32_e32 v18, v2
	v_mov_b32_e32 v19, v2
	v_mov_b32_e32 v20, v2
	v_mov_b32_e32 v21, v2
	v_mov_b32_e32 v22, v2
	v_mov_b32_e32 v23, v2
	v_mov_b32_e32 v24, v2
	v_mov_b32_e32 v25, v2
	v_mov_b32_e32 v26, v2
	v_mov_b32_e32 v27, v2
	v_mov_b32_e32 v28, v2
	v_mov_b32_e32 v29, v2
	v_mov_b32_e32 v30, v2
	v_mov_b32_e32 v31, v2
	v_mov_b32_e32 v32, v2
	v_mov_b32_e32 v33, v2
	v_mov_b32_e32 v66, v2
	v_mov_b32_e32 v67, v2
	v_mov_b32_e32 v68, v2
	v_mov_b32_e32 v69, v2
	v_mov_b32_e32 v70, v2
	v_mov_b32_e32 v71, v2
	v_mov_b32_e32 v72, v2
	v_mov_b32_e32 v73, v2
	v_mov_b32_e32 v74, v2
	v_mov_b32_e32 v75, v2
	v_mov_b32_e32 v76, v2
	v_mov_b32_e32 v77, v2
	v_mov_b32_e32 v78, v2
	v_mov_b32_e32 v79, v2
	v_mov_b32_e32 v80, v2
	v_mov_b32_e32 v81, v2
	v_mov_b32_e32 v82, v2
	v_mov_b32_e32 v83, v2
	v_mov_b32_e32 v84, v2
	v_mov_b32_e32 v85, v2
	v_mov_b32_e32 v86, v2
	v_mov_b32_e32 v87, v2
	v_mov_b32_e32 v88, v2
	v_mov_b32_e32 v89, v2
	v_mov_b32_e32 v90, v2
	v_mov_b32_e32 v91, v2
	v_mov_b32_e32 v92, v2
	v_mov_b32_e32 v93, v2
	v_mov_b32_e32 v94, v2
	v_mov_b32_e32 v95, v2
	v_mov_b32_e32 v96, v2
	v_mov_b32_e32 v97, v2
	v_mov_b32_e32 v34, v2
	v_mov_b32_e32 v35, v2
	v_mov_b32_e32 v36, v2
	v_mov_b32_e32 v37, v2
	v_mov_b32_e32 v38, v2
	v_mov_b32_e32 v39, v2
	v_mov_b32_e32 v40, v2
	v_mov_b32_e32 v41, v2
	v_mov_b32_e32 v42, v2
	v_mov_b32_e32 v43, v2
	v_mov_b32_e32 v44, v2
	v_mov_b32_e32 v45, v2
	v_mov_b32_e32 v46, v2
	v_mov_b32_e32 v47, v2
	v_mov_b32_e32 v48, v2
	v_mov_b32_e32 v49, v2
	v_mov_b32_e32 v50, v2
	v_mov_b32_e32 v51, v2
	v_mov_b32_e32 v52, v2
	v_mov_b32_e32 v53, v2
	v_mov_b32_e32 v54, v2
	v_mov_b32_e32 v55, v2
	v_mov_b32_e32 v56, v2
	v_mov_b32_e32 v57, v2
	v_mov_b32_e32 v58, v2
	v_mov_b32_e32 v59, v2
	v_mov_b32_e32 v60, v2
	v_mov_b32_e32 v61, v2
	v_mov_b32_e32 v62, v2
	v_mov_b32_e32 v63, v2
	v_mov_b32_e32 v64, v2
	v_mov_b32_e32 v65, v2
	v_mov_b32_e32 v98, v2
	v_mov_b32_e32 v99, v2
	v_mov_b32_e32 v100, v2
	v_mov_b32_e32 v101, v2
	v_mov_b32_e32 v102, v2
	v_mov_b32_e32 v103, v2
	v_mov_b32_e32 v104, v2
	v_mov_b32_e32 v105, v2
	v_mov_b32_e32 v106, v2
	v_mov_b32_e32 v107, v2
	v_mov_b32_e32 v108, v2
	v_mov_b32_e32 v109, v2
	v_mov_b32_e32 v110, v2
	v_mov_b32_e32 v111, v2
	v_mov_b32_e32 v112, v2
	v_mov_b32_e32 v113, v2
	v_mov_b32_e32 v114, v2
	v_mov_b32_e32 v115, v2
	v_mov_b32_e32 v116, v2
	v_mov_b32_e32 v117, v2
	v_mov_b32_e32 v118, v2
	v_mov_b32_e32 v119, v2
	v_mov_b32_e32 v120, v2
	v_mov_b32_e32 v121, v2
	v_mov_b32_e32 v122, v2
	v_mov_b32_e32 v123, v2
	v_mov_b32_e32 v124, v2
	v_mov_b32_e32 v125, v2
	v_mov_b32_e32 v126, v2
	v_mov_b32_e32 v127, v2
	v_mov_b32_e32 v128, v2
	v_mov_b32_e32 v129, v2
	s_branch .LBB0_471

.LBB0_691:
	s_ashr_i32 s15, s14, 31
	s_lshl_b64 s[16:17], s[14:15], 19
	s_add_u32 s16, s82, s16
	s_addc_u32 s17, s83, s17
	s_and_b64 s[18:19], s[6:7], exec
	s_cselect_b32 s15, s17, s5
	s_cselect_b32 s46, s16, s4
	s_ashr_i32 s11, s10, 31
	s_lshl_b64 s[18:19], s[10:11], 19
	s_add_u32 s18, s34, s18
	s_addc_u32 s19, s35, s19
	s_and_b64 s[28:29], s[6:7], exec
	s_cselect_b32 s11, s19, s21
	s_cselect_b32 s47, s18, s20
	s_add_u32 s4, s4, 0x40080
	s_addc_u32 s5, s5, 0
	s_add_u32 s48, s20, 0x100
	s_addc_u32 s49, s21, 0
	s_mov_b32 s50, -2
	s_add_u32 s20, s4, 0xfffc0080
	s_addc_u32 s21, s5, -1
	s_add_i32 s51, 0, 0x10000
	s_cmp_eq_u32 s50, 12
	s_cselect_b32 s29, s15, s21
	s_cselect_b32 s28, s46, s20
	v_add_u32_e32 v140, s51, v143
	s_cselect_b32 s21, s11, s49
	s_cselect_b32 s20, s47, s48
	s_add_i32 s54, 0, 0x14000
	ds_read_b128 v[146:149], v140
	ds_read_b128 v[150:153], v140 offset:1024
	ds_read_b128 v[154:157], v140 offset:2048
	ds_read_b128 v[158:161], v140 offset:3072
	v_add_u32_e32 v140, s54, v143
	ds_read_b128 v[162:165], v140
	ds_read_b128 v[166:169], v140 offset:1024
	ds_read_b128 v[170:173], v140 offset:2048
	ds_read_b128 v[174:177], v140 offset:3072
	v_lshl_add_u64 v[140:141], s[4:5], 0, v[136:137]
	s_add_i32 m0, s38, 0xc000
	ds_read_b128 v[178:181], v145
	ds_read_b128 v[182:185], v145 offset:1024
	ds_read_b128 v[186:189], v145 offset:2048
	ds_read_b128 v[190:193], v145 offset:3072
	ds_read_b128 v[202:205], v145 offset:4096
	ds_read_b128 v[206:209], v145 offset:5120
	ds_read_b128 v[220:223], v145 offset:6144
	ds_read_b128 v[224:227], v145 offset:7168
	global_load_lds_dwordx4 v[140:141], off
	v_lshl_add_u64 v[140:141], s[4:5], 0, v[138:139]
	s_add_i32 m0, s38, 0xe000
	s_nop 0
	global_load_lds_dwordx4 v[140:141], off
	s_waitcnt vmcnt(8)
	s_waitcnt lgkmcnt(0)
	s_barrier
	s_setprio 1
	s_waitcnt lgkmcnt(0)
	v_mfma_f32_16x16x32_bf16 v[126:129], v[146:149], v[178:181], 0
	v_mfma_f32_16x16x32_bf16 v[118:121], v[154:157], v[178:181], 0
	v_mfma_f32_16x16x32_bf16 v[110:113], v[146:149], v[186:189], 0
	v_mfma_f32_16x16x32_bf16 v[102:105], v[154:157], v[186:189], 0
	v_mfma_f32_16x16x32_bf16 v[94:97], v[146:149], v[202:205], 0
	v_mfma_f32_16x16x32_bf16 v[86:89], v[154:157], v[202:205], 0
	v_mfma_f32_16x16x32_bf16 v[78:81], v[146:149], v[220:223], 0
	v_mfma_f32_16x16x32_bf16 v[70:73], v[154:157], v[220:223], 0
	v_mfma_f32_16x16x32_bf16 v[126:129], v[150:153], v[182:185], v[126:129]
	v_mfma_f32_16x16x32_bf16 v[118:121], v[158:161], v[182:185], v[118:121]
	v_mfma_f32_16x16x32_bf16 v[110:113], v[150:153], v[190:193], v[110:113]
	v_mfma_f32_16x16x32_bf16 v[102:105], v[158:161], v[190:193], v[102:105]
	v_mfma_f32_16x16x32_bf16 v[94:97], v[150:153], v[206:209], v[94:97]
	v_mfma_f32_16x16x32_bf16 v[86:89], v[158:161], v[206:209], v[86:89]
	v_mfma_f32_16x16x32_bf16 v[78:81], v[150:153], v[224:227], v[78:81]
	v_mfma_f32_16x16x32_bf16 v[70:73], v[158:161], v[224:227], v[70:73]
	v_mfma_f32_16x16x32_bf16 v[122:125], v[162:165], v[178:181], 0
	v_mfma_f32_16x16x32_bf16 v[114:117], v[170:173], v[178:181], 0
	v_mfma_f32_16x16x32_bf16 v[106:109], v[162:165], v[186:189], 0
	v_mfma_f32_16x16x32_bf16 v[98:101], v[170:173], v[186:189], 0
	v_mfma_f32_16x16x32_bf16 v[90:93], v[162:165], v[202:205], 0
	v_mfma_f32_16x16x32_bf16 v[82:85], v[170:173], v[202:205], 0
	v_mfma_f32_16x16x32_bf16 v[74:77], v[162:165], v[220:223], 0
	v_mfma_f32_16x16x32_bf16 v[66:69], v[170:173], v[220:223], 0
	v_mfma_f32_16x16x32_bf16 v[122:125], v[166:169], v[182:185], v[122:125]
	v_mfma_f32_16x16x32_bf16 v[114:117], v[174:177], v[182:185], v[114:117]
	v_mfma_f32_16x16x32_bf16 v[106:109], v[166:169], v[190:193], v[106:109]
	v_mfma_f32_16x16x32_bf16 v[98:101], v[174:177], v[190:193], v[98:101]
	v_mfma_f32_16x16x32_bf16 v[90:93], v[166:169], v[206:209], v[90:93]
	v_mfma_f32_16x16x32_bf16 v[82:85], v[174:177], v[206:209], v[82:85]
	v_mfma_f32_16x16x32_bf16 v[74:77], v[166:169], v[224:227], v[74:77]
	v_mfma_f32_16x16x32_bf16 v[66:69], v[174:177], v[224:227], v[66:69]
	s_setprio 0
	s_barrier
	s_add_i32 s51, s51, s36
	v_lshl_add_u64 v[140:141], s[20:21], 0, v[0:1]
	s_mov_b32 m0, s51
	ds_read_b128 v[178:181], v145 offset:16384
	ds_read_b128 v[182:185], v145 offset:17408
	ds_read_b128 v[186:189], v145 offset:18432
	ds_read_b128 v[190:193], v145 offset:19456
	ds_read_b128 v[202:205], v145 offset:20480
	ds_read_b128 v[206:209], v145 offset:21504
	ds_read_b128 v[220:223], v145 offset:22528
	ds_read_b128 v[224:227], v145 offset:23552
	global_load_lds_dwordx4 v[140:141], off
	s_add_i32 m0, s51, 0x2000
	s_add_u32 s52, s20, 0x40000
	v_lshl_add_u64 v[194:195], s[20:21], 0, v[130:131]
	s_addc_u32 s53, s21, 0
	s_add_i32 s51, s54, s36
	global_load_lds_dwordx4 v[194:195], off
	v_lshl_add_u64 v[198:199], s[52:53], 0, v[0:1]
	s_mov_b32 m0, s51
	v_lshl_add_u64 v[200:201], s[28:29], 0, v[132:133]
	global_load_lds_dwordx4 v[198:199], off
	v_lshl_add_u64 v[198:199], s[52:53], 0, v[130:131]
	s_add_i32 m0, s51, 0x2000
	s_nop 0
	global_load_lds_dwordx4 v[198:199], off
	v_lshl_add_u64 v[198:199], s[28:29], 0, v[134:135]
	s_mov_b32 m0, s38
	s_nop 0
	global_load_lds_dwordx4 v[198:199], off
	s_mov_b32 m0, s39
	s_nop 0
	global_load_lds_dwordx4 v[200:201], off
	s_waitcnt vmcnt(8)
	s_waitcnt lgkmcnt(0)
	s_barrier
	s_setprio 1
	s_waitcnt lgkmcnt(0)
	v_mfma_f32_16x16x32_bf16 v[62:65], v[146:149], v[178:181], 0
	v_mfma_f32_16x16x32_bf16 v[54:57], v[154:157], v[178:181], 0
	v_mfma_f32_16x16x32_bf16 v[46:49], v[146:149], v[186:189], 0
	v_mfma_f32_16x16x32_bf16 v[38:41], v[154:157], v[186:189], 0
	v_mfma_f32_16x16x32_bf16 v[30:33], v[146:149], v[202:205], 0
	v_mfma_f32_16x16x32_bf16 v[22:25], v[154:157], v[202:205], 0
	v_mfma_f32_16x16x32_bf16 v[14:17], v[146:149], v[220:223], 0
	v_mfma_f32_16x16x32_bf16 v[6:9], v[154:157], v[220:223], 0
	v_mfma_f32_16x16x32_bf16 v[62:65], v[150:153], v[182:185], v[62:65]
	v_mfma_f32_16x16x32_bf16 v[54:57], v[158:161], v[182:185], v[54:57]
	v_mfma_f32_16x16x32_bf16 v[46:49], v[150:153], v[190:193], v[46:49]
	v_mfma_f32_16x16x32_bf16 v[38:41], v[158:161], v[190:193], v[38:41]
	v_mfma_f32_16x16x32_bf16 v[30:33], v[150:153], v[206:209], v[30:33]
	v_mfma_f32_16x16x32_bf16 v[22:25], v[158:161], v[206:209], v[22:25]
	v_mfma_f32_16x16x32_bf16 v[14:17], v[150:153], v[224:227], v[14:17]
	v_mfma_f32_16x16x32_bf16 v[6:9], v[158:161], v[224:227], v[6:9]
	v_mfma_f32_16x16x32_bf16 v[58:61], v[162:165], v[178:181], 0
	v_mfma_f32_16x16x32_bf16 v[50:53], v[170:173], v[178:181], 0
	v_mfma_f32_16x16x32_bf16 v[42:45], v[162:165], v[186:189], 0
	v_mfma_f32_16x16x32_bf16 v[34:37], v[170:173], v[186:189], 0
	v_mfma_f32_16x16x32_bf16 v[26:29], v[162:165], v[202:205], 0
	v_mfma_f32_16x16x32_bf16 v[18:21], v[170:173], v[202:205], 0
	v_mfma_f32_16x16x32_bf16 v[10:13], v[162:165], v[220:223], 0
	v_mfma_f32_16x16x32_bf16 v[2:5], v[170:173], v[220:223], 0
	v_mfma_f32_16x16x32_bf16 v[58:61], v[166:169], v[182:185], v[58:61]
	v_mfma_f32_16x16x32_bf16 v[50:53], v[174:177], v[182:185], v[50:53]
	v_mfma_f32_16x16x32_bf16 v[42:45], v[166:169], v[190:193], v[42:45]
	v_mfma_f32_16x16x32_bf16 v[34:37], v[174:177], v[190:193], v[34:37]
	v_mfma_f32_16x16x32_bf16 v[26:29], v[166:169], v[206:209], v[26:29]
	v_mfma_f32_16x16x32_bf16 v[18:21], v[174:177], v[206:209], v[18:21]
	v_mfma_f32_16x16x32_bf16 v[10:13], v[166:169], v[224:227], v[10:13]
	v_mfma_f32_16x16x32_bf16 v[2:5], v[174:177], v[224:227], v[2:5]
	s_setprio 0
	s_barrier
	s_add_i32 s51, 0, 0x18000
	s_add_i32 s52, 0, 0x1c000
	v_add_u32_e32 v158, s51, v143
	v_add_u32_e32 v174, s52, v143
	ds_read_b128 v[146:149], v158
	ds_read_b128 v[150:153], v158 offset:1024
	ds_read_b128 v[154:157], v158 offset:2048
	ds_read_b128 v[158:161], v158 offset:3072
	ds_read_b128 v[162:165], v174
	ds_read_b128 v[166:169], v174 offset:1024
	ds_read_b128 v[170:173], v174 offset:2048
	ds_read_b128 v[174:177], v174 offset:3072
	s_add_u32 s28, s28, 0x40000
	s_addc_u32 s29, s29, 0
	s_mov_b32 m0, s40
	v_lshl_add_u64 v[210:211], s[28:29], 0, v[134:135]
	ds_read_b128 v[178:181], v145 offset:32768
	ds_read_b128 v[182:185], v145 offset:33792
	ds_read_b128 v[186:189], v145 offset:34816
	ds_read_b128 v[190:193], v145 offset:35840
	ds_read_b128 v[202:205], v145 offset:36864
	ds_read_b128 v[206:209], v145 offset:37888
	ds_read_b128 v[220:223], v145 offset:38912
	ds_read_b128 v[224:227], v145 offset:39936
	global_load_lds_dwordx4 v[210:211], off
	v_lshl_add_u64 v[210:211], s[28:29], 0, v[132:133]
	s_mov_b32 m0, s41
	s_nop 0
	global_load_lds_dwordx4 v[210:211], off
	s_waitcnt vmcnt(8)
	s_waitcnt lgkmcnt(0)
	s_barrier
	s_setprio 1
	s_waitcnt lgkmcnt(0)
	v_mfma_f32_16x16x32_bf16 v[126:129], v[146:149], v[178:181], v[126:129]
	v_mfma_f32_16x16x32_bf16 v[118:121], v[154:157], v[178:181], v[118:121]
	v_mfma_f32_16x16x32_bf16 v[110:113], v[146:149], v[186:189], v[110:113]
	v_mfma_f32_16x16x32_bf16 v[102:105], v[154:157], v[186:189], v[102:105]
	v_mfma_f32_16x16x32_bf16 v[94:97], v[146:149], v[202:205], v[94:97]
	v_mfma_f32_16x16x32_bf16 v[86:89], v[154:157], v[202:205], v[86:89]
	v_mfma_f32_16x16x32_bf16 v[78:81], v[146:149], v[220:223], v[78:81]
	v_mfma_f32_16x16x32_bf16 v[70:73], v[154:157], v[220:223], v[70:73]
	v_mfma_f32_16x16x32_bf16 v[126:129], v[150:153], v[182:185], v[126:129]
	v_mfma_f32_16x16x32_bf16 v[118:121], v[158:161], v[182:185], v[118:121]
	v_mfma_f32_16x16x32_bf16 v[110:113], v[150:153], v[190:193], v[110:113]
	v_mfma_f32_16x16x32_bf16 v[102:105], v[158:161], v[190:193], v[102:105]
	v_mfma_f32_16x16x32_bf16 v[94:97], v[150:153], v[206:209], v[94:97]
	v_mfma_f32_16x16x32_bf16 v[86:89], v[158:161], v[206:209], v[86:89]
	v_mfma_f32_16x16x32_bf16 v[78:81], v[150:153], v[224:227], v[78:81]
	v_mfma_f32_16x16x32_bf16 v[70:73], v[158:161], v[224:227], v[70:73]
	v_mfma_f32_16x16x32_bf16 v[122:125], v[162:165], v[178:181], v[122:125]
	v_mfma_f32_16x16x32_bf16 v[114:117], v[170:173], v[178:181], v[114:117]
	v_mfma_f32_16x16x32_bf16 v[106:109], v[162:165], v[186:189], v[106:109]
	v_mfma_f32_16x16x32_bf16 v[98:101], v[170:173], v[186:189], v[98:101]
	v_mfma_f32_16x16x32_bf16 v[90:93], v[162:165], v[202:205], v[90:93]
	v_mfma_f32_16x16x32_bf16 v[82:85], v[170:173], v[202:205], v[82:85]
	v_mfma_f32_16x16x32_bf16 v[74:77], v[162:165], v[220:223], v[74:77]
	v_mfma_f32_16x16x32_bf16 v[66:69], v[170:173], v[220:223], v[66:69]
	v_mfma_f32_16x16x32_bf16 v[122:125], v[166:169], v[182:185], v[122:125]
	v_mfma_f32_16x16x32_bf16 v[114:117], v[174:177], v[182:185], v[114:117]
	v_mfma_f32_16x16x32_bf16 v[106:109], v[166:169], v[190:193], v[106:109]
	v_mfma_f32_16x16x32_bf16 v[98:101], v[174:177], v[190:193], v[98:101]
	v_mfma_f32_16x16x32_bf16 v[90:93], v[166:169], v[206:209], v[90:93]
	v_mfma_f32_16x16x32_bf16 v[82:85], v[174:177], v[206:209], v[82:85]
	v_mfma_f32_16x16x32_bf16 v[74:77], v[166:169], v[224:227], v[74:77]
	v_mfma_f32_16x16x32_bf16 v[66:69], v[174:177], v[224:227], v[66:69]
	s_setprio 0
	s_barrier
	s_add_i32 s28, s51, s36
	v_lshl_add_u64 v[140:141], v[140:141], 0, s[84:85]
	s_mov_b32 m0, s28
	ds_read_b128 v[178:181], v145 offset:49152
	ds_read_b128 v[182:185], v145 offset:50176
	ds_read_b128 v[186:189], v145 offset:51200
	ds_read_b128 v[190:193], v145 offset:52224
	ds_read_b128 v[202:205], v145 offset:53248
	ds_read_b128 v[206:209], v145 offset:54272
	ds_read_b128 v[220:223], v145 offset:55296
	ds_read_b128 v[224:227], v145 offset:56320
	global_load_lds_dwordx4 v[140:141], off
	s_add_i32 m0, s28, 0x2000
	s_add_u32 s20, s20, 0x40080
	v_lshl_add_u64 v[140:141], v[194:195], 0, s[84:85]
	s_addc_u32 s21, s21, 0
	s_add_i32 s28, s52, s36
	global_load_lds_dwordx4 v[140:141], off
	v_lshl_add_u64 v[140:141], s[20:21], 0, v[0:1]
	s_mov_b32 m0, s28
	s_nop 0
	global_load_lds_dwordx4 v[140:141], off
	v_lshl_add_u64 v[140:141], s[20:21], 0, v[130:131]
	s_add_i32 m0, s28, 0x2000
	s_nop 0
	global_load_lds_dwordx4 v[140:141], off
	v_lshl_add_u64 v[140:141], v[198:199], 0, s[84:85]
	s_mov_b32 m0, s76
	s_nop 0
	global_load_lds_dwordx4 v[140:141], off
	v_lshl_add_u64 v[140:141], v[200:201], 0, s[84:85]
	s_mov_b32 m0, s77
	s_nop 0
	global_load_lds_dwordx4 v[140:141], off
	s_waitcnt vmcnt(8)
	s_waitcnt lgkmcnt(0)
	s_barrier
	s_setprio 1
	s_waitcnt lgkmcnt(0)
	v_mfma_f32_16x16x32_bf16 v[62:65], v[146:149], v[178:181], v[62:65]
	v_mfma_f32_16x16x32_bf16 v[54:57], v[154:157], v[178:181], v[54:57]
	v_mfma_f32_16x16x32_bf16 v[46:49], v[146:149], v[186:189], v[46:49]
	v_mfma_f32_16x16x32_bf16 v[38:41], v[154:157], v[186:189], v[38:41]
	v_mfma_f32_16x16x32_bf16 v[30:33], v[146:149], v[202:205], v[30:33]
	v_mfma_f32_16x16x32_bf16 v[22:25], v[154:157], v[202:205], v[22:25]
	v_mfma_f32_16x16x32_bf16 v[14:17], v[146:149], v[220:223], v[14:17]
	v_mfma_f32_16x16x32_bf16 v[6:9], v[154:157], v[220:223], v[6:9]
	v_mfma_f32_16x16x32_bf16 v[62:65], v[150:153], v[182:185], v[62:65]
	v_mfma_f32_16x16x32_bf16 v[54:57], v[158:161], v[182:185], v[54:57]
	v_mfma_f32_16x16x32_bf16 v[46:49], v[150:153], v[190:193], v[46:49]
	v_mfma_f32_16x16x32_bf16 v[38:41], v[158:161], v[190:193], v[38:41]
	v_mfma_f32_16x16x32_bf16 v[30:33], v[150:153], v[206:209], v[30:33]
	v_mfma_f32_16x16x32_bf16 v[22:25], v[158:161], v[206:209], v[22:25]
	v_mfma_f32_16x16x32_bf16 v[14:17], v[150:153], v[224:227], v[14:17]
	v_mfma_f32_16x16x32_bf16 v[6:9], v[158:161], v[224:227], v[6:9]
	v_mfma_f32_16x16x32_bf16 v[58:61], v[162:165], v[178:181], v[58:61]
	v_mfma_f32_16x16x32_bf16 v[50:53], v[170:173], v[178:181], v[50:53]
	v_mfma_f32_16x16x32_bf16 v[42:45], v[162:165], v[186:189], v[42:45]
	v_mfma_f32_16x16x32_bf16 v[34:37], v[170:173], v[186:189], v[34:37]
	v_mfma_f32_16x16x32_bf16 v[26:29], v[162:165], v[202:205], v[26:29]
	v_mfma_f32_16x16x32_bf16 v[18:21], v[170:173], v[202:205], v[18:21]
	v_mfma_f32_16x16x32_bf16 v[10:13], v[162:165], v[220:223], v[10:13]
	v_mfma_f32_16x16x32_bf16 v[2:5], v[170:173], v[220:223], v[2:5]
	v_mfma_f32_16x16x32_bf16 v[58:61], v[166:169], v[182:185], v[58:61]
	v_mfma_f32_16x16x32_bf16 v[50:53], v[174:177], v[182:185], v[50:53]
	v_mfma_f32_16x16x32_bf16 v[42:45], v[166:169], v[190:193], v[42:45]
	v_mfma_f32_16x16x32_bf16 v[34:37], v[174:177], v[190:193], v[34:37]
	v_mfma_f32_16x16x32_bf16 v[26:29], v[166:169], v[206:209], v[26:29]
	v_mfma_f32_16x16x32_bf16 v[18:21], v[174:177], v[206:209], v[18:21]
	v_mfma_f32_16x16x32_bf16 v[10:13], v[166:169], v[224:227], v[10:13]
	v_mfma_f32_16x16x32_bf16 v[2:5], v[174:177], v[224:227], v[2:5]
	s_setprio 0
	s_barrier
	s_add_i32 s50, s50, 2
	s_add_u32 s4, s4, 0x100
	s_addc_u32 s5, s5, 0
	s_add_u32 s48, s48, 0x100
	s_addc_u32 s49, s49, 0
	s_cmp_gt_u32 s50, 13
	s_cbranch_scc1 .Lpeel_exit_swi
.LBB0_692:
	s_add_u32 s20, s4, 0xfffc0080
	s_addc_u32 s21, s5, -1
	s_add_i32 s51, 0, 0x10000
	s_cmp_eq_u32 s50, 12
	s_cselect_b32 s29, s15, s21
	s_cselect_b32 s28, s46, s20
	v_add_u32_e32 v140, s51, v143
	s_cselect_b32 s21, s11, s49
	s_cselect_b32 s20, s47, s48
	s_add_i32 s54, 0, 0x14000
	ds_read_b128 v[146:149], v140
	ds_read_b128 v[150:153], v140 offset:1024
	ds_read_b128 v[154:157], v140 offset:2048
	ds_read_b128 v[158:161], v140 offset:3072
	v_add_u32_e32 v140, s54, v143
	ds_read_b128 v[162:165], v140
	ds_read_b128 v[166:169], v140 offset:1024
	ds_read_b128 v[170:173], v140 offset:2048
	ds_read_b128 v[174:177], v140 offset:3072
	v_lshl_add_u64 v[140:141], s[4:5], 0, v[136:137]
	s_add_i32 m0, s38, 0xc000
	ds_read_b128 v[178:181], v145
	ds_read_b128 v[182:185], v145 offset:1024
	ds_read_b128 v[186:189], v145 offset:2048
	ds_read_b128 v[190:193], v145 offset:3072
	ds_read_b128 v[202:205], v145 offset:4096
	ds_read_b128 v[206:209], v145 offset:5120
	ds_read_b128 v[220:223], v145 offset:6144
	ds_read_b128 v[224:227], v145 offset:7168
	global_load_lds_dwordx4 v[140:141], off
	v_lshl_add_u64 v[140:141], s[4:5], 0, v[138:139]
	s_add_i32 m0, s38, 0xe000
	s_nop 0
	global_load_lds_dwordx4 v[140:141], off
	s_waitcnt vmcnt(8)
	s_waitcnt lgkmcnt(0)
	s_barrier
	s_setprio 1
	s_waitcnt lgkmcnt(0)
	v_mfma_f32_16x16x32_bf16 v[126:129], v[146:149], v[178:181], v[126:129]
	v_mfma_f32_16x16x32_bf16 v[118:121], v[154:157], v[178:181], v[118:121]
	v_mfma_f32_16x16x32_bf16 v[110:113], v[146:149], v[186:189], v[110:113]
	v_mfma_f32_16x16x32_bf16 v[102:105], v[154:157], v[186:189], v[102:105]
	v_mfma_f32_16x16x32_bf16 v[94:97], v[146:149], v[202:205], v[94:97]
	v_mfma_f32_16x16x32_bf16 v[86:89], v[154:157], v[202:205], v[86:89]
	v_mfma_f32_16x16x32_bf16 v[78:81], v[146:149], v[220:223], v[78:81]
	v_mfma_f32_16x16x32_bf16 v[70:73], v[154:157], v[220:223], v[70:73]
	v_mfma_f32_16x16x32_bf16 v[126:129], v[150:153], v[182:185], v[126:129]
	v_mfma_f32_16x16x32_bf16 v[118:121], v[158:161], v[182:185], v[118:121]
	v_mfma_f32_16x16x32_bf16 v[110:113], v[150:153], v[190:193], v[110:113]
	v_mfma_f32_16x16x32_bf16 v[102:105], v[158:161], v[190:193], v[102:105]
	v_mfma_f32_16x16x32_bf16 v[94:97], v[150:153], v[206:209], v[94:97]
	v_mfma_f32_16x16x32_bf16 v[86:89], v[158:161], v[206:209], v[86:89]
	v_mfma_f32_16x16x32_bf16 v[78:81], v[150:153], v[224:227], v[78:81]
	v_mfma_f32_16x16x32_bf16 v[70:73], v[158:161], v[224:227], v[70:73]
	v_mfma_f32_16x16x32_bf16 v[122:125], v[162:165], v[178:181], v[122:125]
	v_mfma_f32_16x16x32_bf16 v[114:117], v[170:173], v[178:181], v[114:117]
	v_mfma_f32_16x16x32_bf16 v[106:109], v[162:165], v[186:189], v[106:109]
	v_mfma_f32_16x16x32_bf16 v[98:101], v[170:173], v[186:189], v[98:101]
	v_mfma_f32_16x16x32_bf16 v[90:93], v[162:165], v[202:205], v[90:93]
	v_mfma_f32_16x16x32_bf16 v[82:85], v[170:173], v[202:205], v[82:85]
	v_mfma_f32_16x16x32_bf16 v[74:77], v[162:165], v[220:223], v[74:77]
	v_mfma_f32_16x16x32_bf16 v[66:69], v[170:173], v[220:223], v[66:69]
	v_mfma_f32_16x16x32_bf16 v[122:125], v[166:169], v[182:185], v[122:125]
	v_mfma_f32_16x16x32_bf16 v[114:117], v[174:177], v[182:185], v[114:117]
	v_mfma_f32_16x16x32_bf16 v[106:109], v[166:169], v[190:193], v[106:109]
	v_mfma_f32_16x16x32_bf16 v[98:101], v[174:177], v[190:193], v[98:101]
	v_mfma_f32_16x16x32_bf16 v[90:93], v[166:169], v[206:209], v[90:93]
	v_mfma_f32_16x16x32_bf16 v[82:85], v[174:177], v[206:209], v[82:85]
	v_mfma_f32_16x16x32_bf16 v[74:77], v[166:169], v[224:227], v[74:77]
	v_mfma_f32_16x16x32_bf16 v[66:69], v[174:177], v[224:227], v[66:69]
	s_setprio 0
	s_barrier
	s_add_i32 s51, s51, s36
	v_lshl_add_u64 v[140:141], s[20:21], 0, v[0:1]
	s_mov_b32 m0, s51
	ds_read_b128 v[178:181], v145 offset:16384
	ds_read_b128 v[182:185], v145 offset:17408
	ds_read_b128 v[186:189], v145 offset:18432
	ds_read_b128 v[190:193], v145 offset:19456
	ds_read_b128 v[202:205], v145 offset:20480
	ds_read_b128 v[206:209], v145 offset:21504
	ds_read_b128 v[220:223], v145 offset:22528
	ds_read_b128 v[224:227], v145 offset:23552
	global_load_lds_dwordx4 v[140:141], off
	s_add_i32 m0, s51, 0x2000
	s_add_u32 s52, s20, 0x40000
	v_lshl_add_u64 v[194:195], s[20:21], 0, v[130:131]
	s_addc_u32 s53, s21, 0
	s_add_i32 s51, s54, s36
	global_load_lds_dwordx4 v[194:195], off
	v_lshl_add_u64 v[198:199], s[52:53], 0, v[0:1]
	s_mov_b32 m0, s51
	v_lshl_add_u64 v[200:201], s[28:29], 0, v[132:133]
	global_load_lds_dwordx4 v[198:199], off
	v_lshl_add_u64 v[198:199], s[52:53], 0, v[130:131]
	s_add_i32 m0, s51, 0x2000
	s_nop 0
	global_load_lds_dwordx4 v[198:199], off
	v_lshl_add_u64 v[198:199], s[28:29], 0, v[134:135]
	s_mov_b32 m0, s38
	s_nop 0
	global_load_lds_dwordx4 v[198:199], off
	s_mov_b32 m0, s39
	s_nop 0
	global_load_lds_dwordx4 v[200:201], off
	s_waitcnt vmcnt(8)
	s_waitcnt lgkmcnt(0)
	s_barrier
	s_setprio 1
	s_waitcnt lgkmcnt(0)
	v_mfma_f32_16x16x32_bf16 v[62:65], v[146:149], v[178:181], v[62:65]
	v_mfma_f32_16x16x32_bf16 v[54:57], v[154:157], v[178:181], v[54:57]
	v_mfma_f32_16x16x32_bf16 v[46:49], v[146:149], v[186:189], v[46:49]
	v_mfma_f32_16x16x32_bf16 v[38:41], v[154:157], v[186:189], v[38:41]
	v_mfma_f32_16x16x32_bf16 v[30:33], v[146:149], v[202:205], v[30:33]
	v_mfma_f32_16x16x32_bf16 v[22:25], v[154:157], v[202:205], v[22:25]
	v_mfma_f32_16x16x32_bf16 v[14:17], v[146:149], v[220:223], v[14:17]
	v_mfma_f32_16x16x32_bf16 v[6:9], v[154:157], v[220:223], v[6:9]
	v_mfma_f32_16x16x32_bf16 v[62:65], v[150:153], v[182:185], v[62:65]
	v_mfma_f32_16x16x32_bf16 v[54:57], v[158:161], v[182:185], v[54:57]
	v_mfma_f32_16x16x32_bf16 v[46:49], v[150:153], v[190:193], v[46:49]
	v_mfma_f32_16x16x32_bf16 v[38:41], v[158:161], v[190:193], v[38:41]
	v_mfma_f32_16x16x32_bf16 v[30:33], v[150:153], v[206:209], v[30:33]
	v_mfma_f32_16x16x32_bf16 v[22:25], v[158:161], v[206:209], v[22:25]
	v_mfma_f32_16x16x32_bf16 v[14:17], v[150:153], v[224:227], v[14:17]
	v_mfma_f32_16x16x32_bf16 v[6:9], v[158:161], v[224:227], v[6:9]
	v_mfma_f32_16x16x32_bf16 v[58:61], v[162:165], v[178:181], v[58:61]
	v_mfma_f32_16x16x32_bf16 v[50:53], v[170:173], v[178:181], v[50:53]
	v_mfma_f32_16x16x32_bf16 v[42:45], v[162:165], v[186:189], v[42:45]
	v_mfma_f32_16x16x32_bf16 v[34:37], v[170:173], v[186:189], v[34:37]
	v_mfma_f32_16x16x32_bf16 v[26:29], v[162:165], v[202:205], v[26:29]
	v_mfma_f32_16x16x32_bf16 v[18:21], v[170:173], v[202:205], v[18:21]
	v_mfma_f32_16x16x32_bf16 v[10:13], v[162:165], v[220:223], v[10:13]
	v_mfma_f32_16x16x32_bf16 v[2:5], v[170:173], v[220:223], v[2:5]
	v_mfma_f32_16x16x32_bf16 v[58:61], v[166:169], v[182:185], v[58:61]
	v_mfma_f32_16x16x32_bf16 v[50:53], v[174:177], v[182:185], v[50:53]
	v_mfma_f32_16x16x32_bf16 v[42:45], v[166:169], v[190:193], v[42:45]
	v_mfma_f32_16x16x32_bf16 v[34:37], v[174:177], v[190:193], v[34:37]
	v_mfma_f32_16x16x32_bf16 v[26:29], v[166:169], v[206:209], v[26:29]
	v_mfma_f32_16x16x32_bf16 v[18:21], v[174:177], v[206:209], v[18:21]
	v_mfma_f32_16x16x32_bf16 v[10:13], v[166:169], v[224:227], v[10:13]
	v_mfma_f32_16x16x32_bf16 v[2:5], v[174:177], v[224:227], v[2:5]
	s_setprio 0
	s_barrier
	s_add_i32 s51, 0, 0x18000
	s_add_i32 s52, 0, 0x1c000
	v_add_u32_e32 v158, s51, v143
	v_add_u32_e32 v174, s52, v143
	ds_read_b128 v[146:149], v158
	ds_read_b128 v[150:153], v158 offset:1024
	ds_read_b128 v[154:157], v158 offset:2048
	ds_read_b128 v[158:161], v158 offset:3072
	ds_read_b128 v[162:165], v174
	ds_read_b128 v[166:169], v174 offset:1024
	ds_read_b128 v[170:173], v174 offset:2048
	ds_read_b128 v[174:177], v174 offset:3072
	s_add_u32 s28, s28, 0x40000
	s_addc_u32 s29, s29, 0
	s_mov_b32 m0, s40
	v_lshl_add_u64 v[210:211], s[28:29], 0, v[134:135]
	ds_read_b128 v[178:181], v145 offset:32768
	ds_read_b128 v[182:185], v145 offset:33792
	ds_read_b128 v[186:189], v145 offset:34816
	ds_read_b128 v[190:193], v145 offset:35840
	ds_read_b128 v[202:205], v145 offset:36864
	ds_read_b128 v[206:209], v145 offset:37888
	ds_read_b128 v[220:223], v145 offset:38912
	ds_read_b128 v[224:227], v145 offset:39936
	global_load_lds_dwordx4 v[210:211], off
	v_lshl_add_u64 v[210:211], s[28:29], 0, v[132:133]
	s_mov_b32 m0, s41
	s_nop 0
	global_load_lds_dwordx4 v[210:211], off
	s_waitcnt vmcnt(8)
	s_waitcnt lgkmcnt(0)
	s_barrier
	s_setprio 1
	s_waitcnt lgkmcnt(0)
	v_mfma_f32_16x16x32_bf16 v[126:129], v[146:149], v[178:181], v[126:129]
	v_mfma_f32_16x16x32_bf16 v[118:121], v[154:157], v[178:181], v[118:121]
	v_mfma_f32_16x16x32_bf16 v[110:113], v[146:149], v[186:189], v[110:113]
	v_mfma_f32_16x16x32_bf16 v[102:105], v[154:157], v[186:189], v[102:105]
	v_mfma_f32_16x16x32_bf16 v[94:97], v[146:149], v[202:205], v[94:97]
	v_mfma_f32_16x16x32_bf16 v[86:89], v[154:157], v[202:205], v[86:89]
	v_mfma_f32_16x16x32_bf16 v[78:81], v[146:149], v[220:223], v[78:81]
	v_mfma_f32_16x16x32_bf16 v[70:73], v[154:157], v[220:223], v[70:73]
	v_mfma_f32_16x16x32_bf16 v[126:129], v[150:153], v[182:185], v[126:129]
	v_mfma_f32_16x16x32_bf16 v[118:121], v[158:161], v[182:185], v[118:121]
	v_mfma_f32_16x16x32_bf16 v[110:113], v[150:153], v[190:193], v[110:113]
	v_mfma_f32_16x16x32_bf16 v[102:105], v[158:161], v[190:193], v[102:105]
	v_mfma_f32_16x16x32_bf16 v[94:97], v[150:153], v[206:209], v[94:97]
	v_mfma_f32_16x16x32_bf16 v[86:89], v[158:161], v[206:209], v[86:89]
	v_mfma_f32_16x16x32_bf16 v[78:81], v[150:153], v[224:227], v[78:81]
	v_mfma_f32_16x16x32_bf16 v[70:73], v[158:161], v[224:227], v[70:73]
	v_mfma_f32_16x16x32_bf16 v[122:125], v[162:165], v[178:181], v[122:125]
	v_mfma_f32_16x16x32_bf16 v[114:117], v[170:173], v[178:181], v[114:117]
	v_mfma_f32_16x16x32_bf16 v[106:109], v[162:165], v[186:189], v[106:109]
	v_mfma_f32_16x16x32_bf16 v[98:101], v[170:173], v[186:189], v[98:101]
	v_mfma_f32_16x16x32_bf16 v[90:93], v[162:165], v[202:205], v[90:93]
	v_mfma_f32_16x16x32_bf16 v[82:85], v[170:173], v[202:205], v[82:85]
	v_mfma_f32_16x16x32_bf16 v[74:77], v[162:165], v[220:223], v[74:77]
	v_mfma_f32_16x16x32_bf16 v[66:69], v[170:173], v[220:223], v[66:69]
	v_mfma_f32_16x16x32_bf16 v[122:125], v[166:169], v[182:185], v[122:125]
	v_mfma_f32_16x16x32_bf16 v[114:117], v[174:177], v[182:185], v[114:117]
	v_mfma_f32_16x16x32_bf16 v[106:109], v[166:169], v[190:193], v[106:109]
	v_mfma_f32_16x16x32_bf16 v[98:101], v[174:177], v[190:193], v[98:101]
	v_mfma_f32_16x16x32_bf16 v[90:93], v[166:169], v[206:209], v[90:93]
	v_mfma_f32_16x16x32_bf16 v[82:85], v[174:177], v[206:209], v[82:85]
	v_mfma_f32_16x16x32_bf16 v[74:77], v[166:169], v[224:227], v[74:77]
	v_mfma_f32_16x16x32_bf16 v[66:69], v[174:177], v[224:227], v[66:69]
	s_setprio 0
	s_barrier
	s_add_i32 s28, s51, s36
	v_lshl_add_u64 v[140:141], v[140:141], 0, s[84:85]
	s_mov_b32 m0, s28
	ds_read_b128 v[178:181], v145 offset:49152
	ds_read_b128 v[182:185], v145 offset:50176
	ds_read_b128 v[186:189], v145 offset:51200
	ds_read_b128 v[190:193], v145 offset:52224
	ds_read_b128 v[202:205], v145 offset:53248
	ds_read_b128 v[206:209], v145 offset:54272
	ds_read_b128 v[220:223], v145 offset:55296
	ds_read_b128 v[224:227], v145 offset:56320
	global_load_lds_dwordx4 v[140:141], off
	s_add_i32 m0, s28, 0x2000
	s_add_u32 s20, s20, 0x40080
	v_lshl_add_u64 v[140:141], v[194:195], 0, s[84:85]
	s_addc_u32 s21, s21, 0
	s_add_i32 s28, s52, s36
	global_load_lds_dwordx4 v[140:141], off
	v_lshl_add_u64 v[140:141], s[20:21], 0, v[0:1]
	s_mov_b32 m0, s28
	s_nop 0
	global_load_lds_dwordx4 v[140:141], off
	v_lshl_add_u64 v[140:141], s[20:21], 0, v[130:131]
	s_add_i32 m0, s28, 0x2000
	s_nop 0
	global_load_lds_dwordx4 v[140:141], off
	v_lshl_add_u64 v[140:141], v[198:199], 0, s[84:85]
	s_mov_b32 m0, s76
	s_nop 0
	global_load_lds_dwordx4 v[140:141], off
	v_lshl_add_u64 v[140:141], v[200:201], 0, s[84:85]
	s_mov_b32 m0, s77
	s_nop 0
	global_load_lds_dwordx4 v[140:141], off
	s_waitcnt vmcnt(8)
	s_waitcnt lgkmcnt(0)
	s_barrier
	s_setprio 1
	s_waitcnt lgkmcnt(0)
	v_mfma_f32_16x16x32_bf16 v[62:65], v[146:149], v[178:181], v[62:65]
	v_mfma_f32_16x16x32_bf16 v[54:57], v[154:157], v[178:181], v[54:57]
	v_mfma_f32_16x16x32_bf16 v[46:49], v[146:149], v[186:189], v[46:49]
	v_mfma_f32_16x16x32_bf16 v[38:41], v[154:157], v[186:189], v[38:41]
	v_mfma_f32_16x16x32_bf16 v[30:33], v[146:149], v[202:205], v[30:33]
	v_mfma_f32_16x16x32_bf16 v[22:25], v[154:157], v[202:205], v[22:25]
	v_mfma_f32_16x16x32_bf16 v[14:17], v[146:149], v[220:223], v[14:17]
	v_mfma_f32_16x16x32_bf16 v[6:9], v[154:157], v[220:223], v[6:9]
	v_mfma_f32_16x16x32_bf16 v[62:65], v[150:153], v[182:185], v[62:65]
	v_mfma_f32_16x16x32_bf16 v[54:57], v[158:161], v[182:185], v[54:57]
	v_mfma_f32_16x16x32_bf16 v[46:49], v[150:153], v[190:193], v[46:49]
	v_mfma_f32_16x16x32_bf16 v[38:41], v[158:161], v[190:193], v[38:41]
	v_mfma_f32_16x16x32_bf16 v[30:33], v[150:153], v[206:209], v[30:33]
	v_mfma_f32_16x16x32_bf16 v[22:25], v[158:161], v[206:209], v[22:25]
	v_mfma_f32_16x16x32_bf16 v[14:17], v[150:153], v[224:227], v[14:17]
	v_mfma_f32_16x16x32_bf16 v[6:9], v[158:161], v[224:227], v[6:9]
	v_mfma_f32_16x16x32_bf16 v[58:61], v[162:165], v[178:181], v[58:61]
	v_mfma_f32_16x16x32_bf16 v[50:53], v[170:173], v[178:181], v[50:53]
	v_mfma_f32_16x16x32_bf16 v[42:45], v[162:165], v[186:189], v[42:45]
	v_mfma_f32_16x16x32_bf16 v[34:37], v[170:173], v[186:189], v[34:37]
	v_mfma_f32_16x16x32_bf16 v[26:29], v[162:165], v[202:205], v[26:29]
	v_mfma_f32_16x16x32_bf16 v[18:21], v[170:173], v[202:205], v[18:21]
	v_mfma_f32_16x16x32_bf16 v[10:13], v[162:165], v[220:223], v[10:13]
	v_mfma_f32_16x16x32_bf16 v[2:5], v[170:173], v[220:223], v[2:5]
	v_mfma_f32_16x16x32_bf16 v[58:61], v[166:169], v[182:185], v[58:61]
	v_mfma_f32_16x16x32_bf16 v[50:53], v[174:177], v[182:185], v[50:53]
	v_mfma_f32_16x16x32_bf16 v[42:45], v[166:169], v[190:193], v[42:45]
	v_mfma_f32_16x16x32_bf16 v[34:37], v[174:177], v[190:193], v[34:37]
	v_mfma_f32_16x16x32_bf16 v[26:29], v[166:169], v[206:209], v[26:29]
	v_mfma_f32_16x16x32_bf16 v[18:21], v[174:177], v[206:209], v[18:21]
	v_mfma_f32_16x16x32_bf16 v[10:13], v[166:169], v[224:227], v[10:13]
	v_mfma_f32_16x16x32_bf16 v[2:5], v[174:177], v[224:227], v[2:5]
	s_setprio 0
	s_barrier
	s_add_i32 s50, s50, 2
	s_add_u32 s4, s4, 0x100
	s_addc_u32 s5, s5, 0
	s_add_u32 s48, s48, 0x100
	s_addc_u32 s49, s49, 0
	s_cmp_gt_u32 s50, 13
	s_cbranch_scc0 .LBB0_692
